# v22 + GELU epilogue row-sum loads hoisted (no per-row-group wait for the previous stores)
# baseline (speedup 1.0000x reference)
; __device__ __forceinline__ unsigned cvt_pk_bf16(float lo, float hi) { unsigned r; asm volatile("v_cvt_pk_bf16_f32 %0, %1, %2" : "=v"(r) : "v"(lo), "v"(hi)); return r; }
; __device__ __forceinline__ f32x2 gelu_pk(f32x2 v) {
;     const f32x2 av = __builtin_elementwise_abs(v), d = av * 0.2316418882f + 1.0f;
;     f32x2 t; t.x = __builtin_amdgcn_rcpf(d.x); t.y = __builtin_amdgcn_rcpf(d.y);
;     f32x2 q = t * 0.5307027145f + (-0.7265760135f); q = q * t + 0.7107068705f; q = q * t + (-0.142248368f); q = q * t + 0.127414796f; q = q * t;
;     const f32x2 s = (v * v) * (-0.72134752044f);
;     f32x2 e; e.x = __builtin_amdgcn_exp2f(s.x); e.y = __builtin_amdgcn_exp2f(s.y);
;     const f32x2 m = v * (q * e), r = v - m;
;     f32x2 o; o.x = v.x < 0.f ? m.x : r.x; o.y = v.y < 0.f ? m.y : r.y; return o;
; }
;     static __device__ __forceinline__ void run(const f32x4 (&acc)[2][2][4][2], const Unit& u, int wr, int wc, int fr, int fq, bf16_t* O, int ldc, const float* ssqA, const float* bvec) {
;         const int b = (u.pm * BM) >> 13; const int row0 = u.pm * BM + wr * 64 + fr; const int col0 = u.pn * BM + wc * 32 + 8 * fq;
;         const float* bp = bvec + ((unsigned)b * (unsigned)ldc + (unsigned)col0);
;         f32x4 bv[2][2];
; #pragma unroll
;         for (int bj = 0; bj < 2; ++bj)
; #pragma unroll
;             for (int n = 0; n < 2; ++n) bv[bj][n] = *(const f32x4*)(bp + bj * HALF + 4 * n);
; #pragma unroll
;         for (int ai = 0; ai < 2; ++ai)
; #pragma unroll
;             for (int m = 0; m < 4; ++m) { const int row = row0 + ai * HALF + m * 16; const float r = row_scale(ssqA, nullptr, row); bf16_t* rowp = O + ((unsigned)row * (unsigned)ldc + (unsigned)col0);
; #pragma unroll
;                 for (int bj = 0; bj < 2; ++bj) { const f32x4 v0 = acc[ai][bj][m][0] * r + bv[bj][0], v1 = acc[ai][bj][m][1] * r + bv[bj][1];
;                     const f32x2 a = gelu_pk((f32x2){v0[0], v0[1]}), b2 = gelu_pk((f32x2){v0[2], v0[3]}), c = gelu_pk((f32x2){v1[0], v1[1]}), d = gelu_pk((f32x2){v1[2], v1[3]});
;                     u32x4 w; w.x = cvt_pk_bf16(a.x, a.y); w.y = cvt_pk_bf16(b2.x, b2.y); w.z = cvt_pk_bf16(c.x, c.y); w.w = cvt_pk_bf16(d.x, d.y);
;                     *(u32x4*)(rowp + bj * HALF) = w; }
;                 asm volatile("" ::: "memory"); }
.LBB0_544:
	s_and_b64 vcc, exec, s[2:3]
	s_cbranch_vccz .LBB0_546
	v_readlane_b32 s2, v251, 34
	v_mov_b32_e32 v132, s86
	s_lshl_b32 s8, s65, 6
	v_mov_b32_e32 v128, s2
	v_readlane_b32 s2, v251, 35
	s_lshl_b32 s10, s64, 5
	s_mov_b64 s[26:27], 0
	v_mov_b32_e32 v129, s2
	ds_read_b32 v134, v128
	ds_read_b64 v[128:129], v129
	v_readlane_b32 s2, v251, 33
	s_waitcnt lgkmcnt(0)
	v_readfirstlane_b32 s9, v134
	v_mov_b32_e32 v130, s2
	ds_read_b64 v[130:131], v130
	ds_read_b64 v[132:133], v132
	v_readfirstlane_b32 s2, v128
	v_readfirstlane_b32 s3, v129
	s_nop 0
	v_mov_b32_e32 v128, s2
	s_waitcnt lgkmcnt(0)
	v_readfirstlane_b32 s2, v130
	v_mov_b32_e32 v129, s3
	v_readfirstlane_b32 s3, v131
	v_mov_b32_e32 v130, s2
	s_lshl_b32 s2, s63, 8
	s_add_i32 s8, s8, s2
	v_or_b32_e32 v134, s8, v230
	v_ashrrev_i32_e32 v135, 31, v134
	v_lshl_add_u64 v[146:147], v[134:135], 2, v[128:129]
	global_load_dword v129, v[146:147], off
	s_lshl_b32 s2, s62, 8
	v_mov_b32_e32 v131, s3
	s_ashr_i32 s3, s63, 5
	s_or_b32 s2, s10, s2
	v_lshl_or_b32 v128, v229, 3, s2
	s_mul_i32 s2, s9, s3
	v_add_u32_e32 v176, s2, v128
	v_lshl_add_u64 v[154:155], v[176:177], 2, v[130:131]
	global_load_dwordx4 v[140:143], v[154:155], off
	global_load_dwordx4 v[136:139], v[154:155], off offset:16
	global_load_dword v198, v[146:147], off offset:64
	global_load_dword v199, v[146:147], off offset:128
	global_load_dword v200, v[146:147], off offset:192
	global_load_dword v201, v[146:147], off offset:512
	global_load_dword v202, v[146:147], off offset:576
	global_load_dword v203, v[146:147], off offset:640
	global_load_dword v204, v[146:147], off offset:704
	s_mov_b32 s2, 0xbf3a00e3
	v_mov_b64_e32 v[144:145], s[2:3]
	v_readfirstlane_b32 s2, v132
	v_readfirstlane_b32 s3, v133
	s_lshl_b32 s8, s9, 4
	s_waitcnt vmcnt(7)
	v_mad_u64_u32 v[148:149], s[10:11], s9, v134, v[128:129]
	v_fmamk_f32 v128, v129, 0x3a800000, v222
	v_rsq_f32_e32 v152, v128
	global_load_dwordx4 v[128:131], v[154:155], off offset:528
	global_load_dwordx4 v[132:135], v[154:155], off offset:512
	v_mov_b32_e32 v149, v177
	v_lshl_add_u64 v[150:151], v[148:149], 1, s[2:3]
	s_mulk_i32 s9, 0x50
	v_pk_fma_f32 v[156:157], v[124:125], v[152:153], v[140:141] op_sel_hi:[1,0,1]
	v_pk_fma_f32 v[154:155], v[126:127], v[152:153], v[142:143] op_sel_hi:[1,0,1]
	v_and_b32_e32 v175, 0x7fffffff, v157
	v_and_b32_e32 v174, 0x7fffffff, v156
	v_and_b32_e32 v185, 0x7fffffff, v155
	v_and_b32_e32 v184, 0x7fffffff, v154
	v_pk_fma_f32 v[174:175], v[174:175], s[96:97], 1.0 op_sel_hi:[1,0,0]
	v_pk_fma_f32 v[172:173], v[120:121], v[152:153], v[136:137] op_sel_hi:[1,0,1]
	v_pk_fma_f32 v[184:185], v[184:185], s[96:97], 1.0 op_sel_hi:[1,0,0]
	v_rcp_f32_e32 v174, v174
	v_rcp_f32_e32 v175, v175
	v_and_b32_e32 v187, 0x7fffffff, v173
	v_and_b32_e32 v186, 0x7fffffff, v172
	v_rcp_f32_e32 v184, v184
	v_rcp_f32_e32 v185, v185
	v_pk_fma_f32 v[186:187], v[186:187], s[96:97], 1.0 op_sel_hi:[1,0,0]
	v_pk_mul_f32 v[182:183], v[156:157], v[156:157]
	v_rcp_f32_e32 v186, v186
	v_rcp_f32_e32 v187, v187
	v_pk_mul_f32 v[180:181], v[154:155], v[154:155]
	v_pk_mul_f32 v[182:183], v[182:183], s[74:75] op_sel_hi:[1,0]
	v_pk_fma_f32 v[192:193], v[174:175], s[98:99], v[144:145] op_sel_hi:[1,0,0]
	v_pk_mul_f32 v[180:181], v[180:181], s[74:75] op_sel_hi:[1,0]
	v_exp_f32_e32 v182, v182
	v_exp_f32_e32 v183, v183
	v_pk_fma_f32 v[194:195], v[184:185], s[98:99], v[144:145] op_sel_hi:[1,0,0]
	v_pk_fma_f32 v[192:193], v[174:175], v[192:193], s[90:91] op_sel_hi:[1,1,0]
	v_pk_mul_f32 v[190:191], v[172:173], v[172:173]
	v_exp_f32_e32 v180, v180
	v_exp_f32_e32 v181, v181
	v_pk_fma_f32 v[194:195], v[184:185], v[194:195], s[90:91] op_sel_hi:[1,1,0]
	v_pk_fma_f32 v[192:193], v[174:175], v[192:193], s[4:5] op_sel_hi:[1,1,0]
	v_pk_mul_f32 v[190:191], v[190:191], s[74:75] op_sel_hi:[1,0]
	v_pk_fma_f32 v[196:197], v[186:187], s[98:99], v[144:145] op_sel_hi:[1,0,0]
	v_pk_fma_f32 v[194:195], v[184:185], v[194:195], s[4:5] op_sel_hi:[1,1,0]
	v_pk_fma_f32 v[192:193], v[174:175], v[192:193], s[78:79] op_sel_hi:[1,1,0]
	v_exp_f32_e32 v190, v190
	v_exp_f32_e32 v191, v191
	v_pk_fma_f32 v[196:197], v[186:187], v[196:197], s[90:91] op_sel_hi:[1,1,0]
	v_pk_fma_f32 v[194:195], v[184:185], v[194:195], s[78:79] op_sel_hi:[1,1,0]
	v_pk_mul_f32 v[174:175], v[174:175], v[192:193]
	v_pk_fma_f32 v[196:197], v[186:187], v[196:197], s[4:5] op_sel_hi:[1,1,0]
	v_pk_mul_f32 v[184:185], v[184:185], v[194:195]
	v_pk_mul_f32 v[174:175], v[182:183], v[174:175]
	v_pk_fma_f32 v[196:197], v[186:187], v[196:197], s[78:79] op_sel_hi:[1,1,0]
	v_pk_mul_f32 v[180:181], v[180:181], v[184:185]
	v_pk_mul_f32 v[184:185], v[156:157], v[174:175]
	v_pk_fma_f32 v[174:175], v[156:157], v[174:175], v[156:157] neg_lo:[1,0,0] neg_hi:[1,0,0]
	v_cmp_gt_f32_e32 vcc, 0, v156
	v_pk_mul_f32 v[186:187], v[186:187], v[196:197]
	v_pk_fma_f32 v[158:159], v[122:123], v[152:153], v[138:139] op_sel_hi:[1,0,1]
	v_cndmask_b32_e32 v149, v174, v184, vcc
	v_cmp_gt_f32_e32 vcc, 0, v157
	v_pk_mul_f32 v[182:183], v[190:191], v[186:187]
	v_pk_mul_f32 v[186:187], v[154:155], v[180:181]
	v_pk_fma_f32 v[180:181], v[154:155], v[180:181], v[154:155] neg_lo:[1,0,0] neg_hi:[1,0,0]
	v_cndmask_b32_e32 v153, v175, v185, vcc
	v_cmp_gt_f32_e32 vcc, 0, v154
	v_and_b32_e32 v154, 0x7fffffff, v158
	v_pk_mul_f32 v[188:189], v[158:159], v[158:159]
	v_cndmask_b32_e32 v174, v180, v186, vcc
	v_cmp_gt_f32_e32 vcc, 0, v155
	v_and_b32_e32 v155, 0x7fffffff, v159
	v_pk_fma_f32 v[154:155], v[154:155], s[96:97], 1.0 op_sel_hi:[1,0,0]
	v_pk_mul_f32 v[190:191], v[172:173], v[182:183]
	v_rcp_f32_e32 v154, v154
	v_rcp_f32_e32 v155, v155
	v_pk_fma_f32 v[182:183], v[172:173], v[182:183], v[172:173] neg_lo:[1,0,0] neg_hi:[1,0,0]
	v_cndmask_b32_e32 v175, v181, v187, vcc
	v_cmp_gt_f32_e32 vcc, 0, v172
	v_pk_fma_f32 v[156:157], v[154:155], s[98:99], v[144:145] op_sel_hi:[1,0,0]
	s_nop 0
	v_cndmask_b32_e32 v176, v182, v190, vcc
	v_cmp_gt_f32_e32 vcc, 0, v173
	v_pk_mul_f32 v[172:173], v[188:189], s[74:75] op_sel_hi:[1,0]
	v_pk_fma_f32 v[156:157], v[154:155], v[156:157], s[90:91] op_sel_hi:[1,1,0]
	v_exp_f32_e32 v172, v172
	v_exp_f32_e32 v173, v173
	v_pk_fma_f32 v[156:157], v[154:155], v[156:157], s[4:5] op_sel_hi:[1,1,0]
	v_cndmask_b32_e32 v180, v183, v191, vcc
	v_pk_fma_f32 v[156:157], v[154:155], v[156:157], s[78:79] op_sel_hi:[1,1,0]
	v_cmp_gt_f32_e32 vcc, 0, v158
	v_pk_mul_f32 v[154:155], v[154:155], v[156:157]
	s_nop 0
	v_pk_mul_f32 v[154:155], v[172:173], v[154:155]
	s_waitcnt vmcnt(1)
; __device__ __forceinline__ unsigned cvt_pk_bf16(float lo, float hi) { unsigned r; asm volatile("v_cvt_pk_bf16_f32 %0, %1, %2" : "=v"(r) : "v"(lo), "v"(hi)); return r; }
; __device__ __forceinline__ f32x2 gelu_pk(f32x2 v) {
;     const f32x2 av = __builtin_elementwise_abs(v), d = av * 0.2316418882f + 1.0f;
;     f32x2 t; t.x = __builtin_amdgcn_rcpf(d.x); t.y = __builtin_amdgcn_rcpf(d.y);
;     f32x2 q = t * 0.5307027145f + (-0.7265760135f); q = q * t + 0.7107068705f; q = q * t + (-0.142248368f); q = q * t + 0.127414796f; q = q * t;
;     const f32x2 s = (v * v) * (-0.72134752044f);
;     f32x2 e; e.x = __builtin_amdgcn_exp2f(s.x); e.y = __builtin_amdgcn_exp2f(s.y);
;     const f32x2 m = v * (q * e), r = v - m;
;     f32x2 o; o.x = v.x < 0.f ? m.x : r.x; o.y = v.y < 0.f ? m.y : r.y; return o;
; }
;     static __device__ __forceinline__ void run(const f32x4 (&acc)[2][2][4][2], const Unit& u, int wr, int wc, int fr, int fq, bf16_t* O, int ldc, const float* ssqA, const float* bvec) {
;     ...
;                 for (int bj = 0; bj < 2; ++bj) { const f32x4 v0 = acc[ai][bj][m][0] * r + bv[bj][0], v1 = acc[ai][bj][m][1] * r + bv[bj][1];
;                     const f32x2 a = gelu_pk((f32x2){v0[0], v0[1]}), b2 = gelu_pk((f32x2){v0[2], v0[3]}), c = gelu_pk((f32x2){v1[0], v1[1]}), d = gelu_pk((f32x2){v1[2], v1[3]});
;                     u32x4 w; w.x = cvt_pk_bf16(a.x, a.y); w.y = cvt_pk_bf16(b2.x, b2.y); w.z = cvt_pk_bf16(c.x, c.y); w.w = cvt_pk_bf16(d.x, d.y);
;                     *(u32x4*)(rowp + bj * HALF) = w; }
	v_pk_fma_f32 v[172:173], v[114:115], v[152:153], v[130:131] op_sel_hi:[1,0,1]
	v_pk_mul_f32 v[156:157], v[158:159], v[154:155]
	v_pk_fma_f32 v[154:155], v[158:159], v[154:155], v[158:159] neg_lo:[1,0,0] neg_hi:[1,0,0]
	s_nop 0
	v_cndmask_b32_e32 v158, v154, v156, vcc
	v_cmp_gt_f32_e32 vcc, 0, v159
	v_cvt_pk_bf16_f32 v154, v149, v153
	s_nop 1
	v_cndmask_b32_e32 v157, v155, v157, vcc
	v_cvt_pk_bf16_f32 v155, v174, v175
	v_cvt_pk_bf16_f32 v156, v176, v180
	v_cvt_pk_bf16_f32 v157, v158, v157
	global_store_dwordx4 v[150:151], v[154:157], off
	s_waitcnt vmcnt(1)
	v_pk_fma_f32 v[158:159], v[118:119], v[152:153], v[134:135] op_sel_hi:[1,0,1]
	v_pk_fma_f32 v[154:155], v[116:117], v[152:153], v[132:133] op_sel_hi:[1,0,1]
	v_and_b32_e32 v183, 0x7fffffff, v159
	v_and_b32_e32 v157, 0x7fffffff, v155
	v_and_b32_e32 v156, 0x7fffffff, v154
	v_pk_fma_f32 v[156:157], v[156:157], s[96:97], 1.0 op_sel_hi:[1,0,0]
	v_pk_mul_f32 v[180:181], v[154:155], v[154:155]
	v_rcp_f32_e32 v156, v156
	v_rcp_f32_e32 v157, v157
	v_pk_mul_f32 v[180:181], v[180:181], s[74:75] op_sel_hi:[1,0]
	v_and_b32_e32 v182, 0x7fffffff, v158
	v_exp_f32_e32 v180, v180
	v_pk_fma_f32 v[174:175], v[156:157], s[98:99], v[144:145] op_sel_hi:[1,0,0]
	v_exp_f32_e32 v181, v181
	v_pk_fma_f32 v[174:175], v[156:157], v[174:175], s[90:91] op_sel_hi:[1,1,0]
	v_pk_fma_f32 v[182:183], v[182:183], s[96:97], 1.0 op_sel_hi:[1,0,0]
	v_pk_fma_f32 v[174:175], v[156:157], v[174:175], s[4:5] op_sel_hi:[1,1,0]
	v_rcp_f32_e32 v182, v182
	v_pk_fma_f32 v[174:175], v[156:157], v[174:175], s[78:79] op_sel_hi:[1,1,0]
	v_rcp_f32_e32 v183, v183
	v_pk_mul_f32 v[156:157], v[156:157], v[174:175]
	v_cmp_gt_f32_e32 vcc, 0, v154
	v_pk_mul_f32 v[156:157], v[180:181], v[156:157]
	v_pk_mul_f32 v[174:175], v[158:159], v[158:159]
	v_pk_mul_f32 v[180:181], v[154:155], v[156:157]
	v_pk_fma_f32 v[156:157], v[154:155], v[156:157], v[154:155] neg_lo:[1,0,0] neg_hi:[1,0,0]
	v_pk_fma_f32 v[152:153], v[112:113], v[152:153], v[128:129] op_sel_hi:[1,0,1]
	v_cndmask_b32_e32 v149, v156, v180, vcc
	v_cmp_gt_f32_e32 vcc, 0, v155
	v_pk_fma_f32 v[154:155], v[182:183], s[98:99], v[144:145] op_sel_hi:[1,0,0]
	s_nop 0
	v_cndmask_b32_e32 v176, v157, v181, vcc
	v_pk_mul_f32 v[156:157], v[174:175], s[74:75] op_sel_hi:[1,0]
	v_pk_fma_f32 v[154:155], v[182:183], v[154:155], s[90:91] op_sel_hi:[1,1,0]
	v_exp_f32_e32 v156, v156
	v_exp_f32_e32 v157, v157
	v_pk_fma_f32 v[154:155], v[182:183], v[154:155], s[4:5] op_sel_hi:[1,1,0]
	v_and_b32_e32 v175, 0x7fffffff, v153
	v_and_b32_e32 v174, 0x7fffffff, v152
	v_pk_fma_f32 v[154:155], v[182:183], v[154:155], s[78:79] op_sel_hi:[1,1,0]
	v_pk_fma_f32 v[174:175], v[174:175], s[96:97], 1.0 op_sel_hi:[1,0,0]
	v_pk_mul_f32 v[154:155], v[182:183], v[154:155]
	v_rcp_f32_e32 v174, v174
	v_rcp_f32_e32 v175, v175
	v_pk_mul_f32 v[154:155], v[156:157], v[154:155]
	v_cmp_gt_f32_e32 vcc, 0, v158
	v_pk_mul_f32 v[156:157], v[158:159], v[154:155]
	v_pk_fma_f32 v[154:155], v[158:159], v[154:155], v[158:159] neg_lo:[1,0,0] neg_hi:[1,0,0]
	s_nop 0
	v_cndmask_b32_e32 v180, v154, v156, vcc
	v_cmp_gt_f32_e32 vcc, 0, v159
	v_pk_mul_f32 v[158:159], v[172:173], v[172:173]
	s_nop 0
	v_cndmask_b32_e32 v181, v155, v157, vcc
	v_pk_fma_f32 v[154:155], v[174:175], s[98:99], v[144:145] op_sel_hi:[1,0,0]
	v_pk_mul_f32 v[156:157], v[152:153], v[152:153]
	v_pk_fma_f32 v[154:155], v[174:175], v[154:155], s[90:91] op_sel_hi:[1,1,0]
	v_pk_mul_f32 v[156:157], v[156:157], s[74:75] op_sel_hi:[1,0]
	v_pk_fma_f32 v[154:155], v[174:175], v[154:155], s[4:5] op_sel_hi:[1,1,0]
	v_exp_f32_e32 v156, v156
	v_exp_f32_e32 v157, v157
	v_pk_fma_f32 v[154:155], v[174:175], v[154:155], s[78:79] op_sel_hi:[1,1,0]
	v_cmp_gt_f32_e32 vcc, 0, v152
	v_pk_mul_f32 v[154:155], v[174:175], v[154:155]
	v_and_b32_e32 v175, 0x7fffffff, v173
	v_and_b32_e32 v174, 0x7fffffff, v172
	v_pk_fma_f32 v[174:175], v[174:175], s[96:97], 1.0 op_sel_hi:[1,0,0]
	v_pk_mul_f32 v[154:155], v[156:157], v[154:155]
	v_rcp_f32_e32 v174, v174
	v_rcp_f32_e32 v175, v175
	v_pk_mul_f32 v[156:157], v[152:153], v[154:155]
	v_pk_fma_f32 v[154:155], v[152:153], v[154:155], v[152:153] neg_lo:[1,0,0] neg_hi:[1,0,0]
	s_nop 0
	v_cndmask_b32_e32 v156, v154, v156, vcc
	v_cmp_gt_f32_e32 vcc, 0, v153
	v_pk_fma_f32 v[152:153], v[174:175], s[98:99], v[144:145] op_sel_hi:[1,0,0]
	s_nop 0
	v_cndmask_b32_e32 v157, v155, v157, vcc
	v_pk_mul_f32 v[154:155], v[158:159], s[74:75] op_sel_hi:[1,0]
	v_pk_fma_f32 v[152:153], v[174:175], v[152:153], s[90:91] op_sel_hi:[1,1,0]
	v_exp_f32_e32 v154, v154
	v_exp_f32_e32 v155, v155
	v_pk_fma_f32 v[152:153], v[174:175], v[152:153], s[4:5] op_sel_hi:[1,1,0]
	v_cmp_gt_f32_e32 vcc, 0, v172
	v_pk_fma_f32 v[152:153], v[174:175], v[152:153], s[78:79] op_sel_hi:[1,1,0]
	s_nop 0
	v_pk_mul_f32 v[152:153], v[174:175], v[152:153]
	s_nop 0
	v_pk_mul_f32 v[152:153], v[154:155], v[152:153]
	s_nop 0
	v_pk_mul_f32 v[154:155], v[172:173], v[152:153]
	v_pk_fma_f32 v[152:153], v[172:173], v[152:153], v[172:173] neg_lo:[1,0,0] neg_hi:[1,0,0]
	s_nop 0
	v_cndmask_b32_e32 v158, v152, v154, vcc
	v_cmp_gt_f32_e32 vcc, 0, v173
	v_cvt_pk_bf16_f32 v152, v149, v176
	v_add_u32_e32 v176, s8, v148
	s_nop 0
	v_cndmask_b32_e32 v155, v153, v155, vcc
	v_cvt_pk_bf16_f32 v153, v180, v181
	v_cvt_pk_bf16_f32 v154, v156, v157
	v_cvt_pk_bf16_f32 v155, v158, v155
	global_store_dwordx4 v[150:151], v[152:155], off offset:256
	s_nop 0
	s_waitcnt vmcnt(10)
; __device__ __forceinline__ unsigned cvt_pk_bf16(float lo, float hi) { unsigned r; asm volatile("v_cvt_pk_bf16_f32 %0, %1, %2" : "=v"(r) : "v"(lo), "v"(hi)); return r; }
; __device__ __forceinline__ f32x2 gelu_pk(f32x2 v) {
;     const f32x2 av = __builtin_elementwise_abs(v), d = av * 0.2316418882f + 1.0f;
;     f32x2 t; t.x = __builtin_amdgcn_rcpf(d.x); t.y = __builtin_amdgcn_rcpf(d.y);
;     f32x2 q = t * 0.5307027145f + (-0.7265760135f); q = q * t + 0.7107068705f; q = q * t + (-0.142248368f); q = q * t + 0.127414796f; q = q * t;
;     const f32x2 s = (v * v) * (-0.72134752044f);
;     f32x2 e; e.x = __builtin_amdgcn_exp2f(s.x); e.y = __builtin_amdgcn_exp2f(s.y);
;     const f32x2 m = v * (q * e), r = v - m;
;     f32x2 o; o.x = v.x < 0.f ? m.x : r.x; o.y = v.y < 0.f ? m.y : r.y; return o;
; }
;     static __device__ __forceinline__ void run(const f32x4 (&acc)[2][2][4][2], const Unit& u, int wr, int wc, int fr, int fq, bf16_t* O, int ldc, const float* ssqA, const float* bvec) {
;     ...
;             for (int m = 0; m < 4; ++m) { const int row = row0 + ai * HALF + m * 16; const float r = row_scale(ssqA, nullptr, row); bf16_t* rowp = O + ((unsigned)row * (unsigned)ldc + (unsigned)col0);
; #pragma unroll
;                 for (int bj = 0; bj < 2; ++bj) { const f32x4 v0 = acc[ai][bj][m][0] * r + bv[bj][0], v1 = acc[ai][bj][m][1] * r + bv[bj][1];
;                     const f32x2 a = gelu_pk((f32x2){v0[0], v0[1]}), b2 = gelu_pk((f32x2){v0[2], v0[3]}), c = gelu_pk((f32x2){v1[0], v1[1]}), d = gelu_pk((f32x2){v1[2], v1[3]});
;                     u32x4 w; w.x = cvt_pk_bf16(a.x, a.y); w.y = cvt_pk_bf16(b2.x, b2.y); w.z = cvt_pk_bf16(c.x, c.y); w.w = cvt_pk_bf16(d.x, d.y);
;                     *(u32x4*)(rowp + bj * HALF) = w; }
	v_fmamk_f32 v149, v198, 0x3a800000, v222
	v_rsq_f32_e32 v154, v149
	v_lshl_add_u64 v[148:149], v[176:177], 1, s[2:3]
	v_add_u32_e32 v176, s8, v176
	v_pk_fma_f32 v[150:151], v[108:109], v[154:155], v[140:141] op_sel_hi:[1,0,1]
	s_nop 0
	v_and_b32_e32 v153, 0x7fffffff, v151
	v_and_b32_e32 v152, 0x7fffffff, v150
	v_pk_fma_f32 v[152:153], v[152:153], s[96:97], 1.0 op_sel_hi:[1,0,0]
	v_pk_mul_f32 v[180:181], v[150:151], v[150:151]
	v_rcp_f32_e32 v152, v152
	v_rcp_f32_e32 v153, v153
	v_pk_mul_f32 v[180:181], v[180:181], s[74:75] op_sel_hi:[1,0]
	v_pk_fma_f32 v[156:157], v[110:111], v[154:155], v[142:143] op_sel_hi:[1,0,1]
	v_exp_f32_e32 v180, v180
	v_pk_fma_f32 v[174:175], v[152:153], s[98:99], v[144:145] op_sel_hi:[1,0,0]
	v_exp_f32_e32 v181, v181
	v_pk_fma_f32 v[174:175], v[152:153], v[174:175], s[90:91] op_sel_hi:[1,1,0]
	v_and_b32_e32 v183, 0x7fffffff, v157
	v_pk_fma_f32 v[174:175], v[152:153], v[174:175], s[4:5] op_sel_hi:[1,1,0]
	v_and_b32_e32 v182, 0x7fffffff, v156
	v_pk_fma_f32 v[174:175], v[152:153], v[174:175], s[78:79] op_sel_hi:[1,1,0]
	v_pk_fma_f32 v[182:183], v[182:183], s[96:97], 1.0 op_sel_hi:[1,0,0]
	v_pk_mul_f32 v[152:153], v[152:153], v[174:175]
	v_rcp_f32_e32 v182, v182
	v_rcp_f32_e32 v183, v183
	v_pk_mul_f32 v[152:153], v[180:181], v[152:153]
	v_cmp_gt_f32_e32 vcc, 0, v150
	v_pk_mul_f32 v[180:181], v[150:151], v[152:153]
	v_pk_fma_f32 v[152:153], v[150:151], v[152:153], v[150:151] neg_lo:[1,0,0] neg_hi:[1,0,0]
	v_pk_fma_f32 v[158:159], v[106:107], v[154:155], v[138:139] op_sel_hi:[1,0,1]
	v_pk_fma_f32 v[172:173], v[104:105], v[154:155], v[136:137] op_sel_hi:[1,0,1]
	v_pk_mul_f32 v[174:175], v[156:157], v[156:157]
	v_cndmask_b32_e32 v155, v152, v180, vcc
	v_cmp_gt_f32_e32 vcc, 0, v151
	v_pk_fma_f32 v[150:151], v[182:183], s[98:99], v[144:145] op_sel_hi:[1,0,0]
	s_nop 0
	v_cndmask_b32_e32 v180, v153, v181, vcc
	v_pk_mul_f32 v[152:153], v[174:175], s[74:75] op_sel_hi:[1,0]
	v_pk_fma_f32 v[150:151], v[182:183], v[150:151], s[90:91] op_sel_hi:[1,1,0]
	v_exp_f32_e32 v152, v152
	v_exp_f32_e32 v153, v153
	v_pk_fma_f32 v[150:151], v[182:183], v[150:151], s[4:5] op_sel_hi:[1,1,0]
	v_and_b32_e32 v175, 0x7fffffff, v173
	v_and_b32_e32 v174, 0x7fffffff, v172
	v_pk_fma_f32 v[150:151], v[182:183], v[150:151], s[78:79] op_sel_hi:[1,1,0]
	v_pk_fma_f32 v[174:175], v[174:175], s[96:97], 1.0 op_sel_hi:[1,0,0]
	v_pk_mul_f32 v[150:151], v[182:183], v[150:151]
	v_rcp_f32_e32 v174, v174
	v_rcp_f32_e32 v175, v175
	v_pk_mul_f32 v[150:151], v[152:153], v[150:151]
	v_cmp_gt_f32_e32 vcc, 0, v156
	v_pk_mul_f32 v[152:153], v[156:157], v[150:151]
	v_pk_fma_f32 v[150:151], v[156:157], v[150:151], v[156:157] neg_lo:[1,0,0] neg_hi:[1,0,0]
	s_nop 0
	v_cndmask_b32_e32 v181, v150, v152, vcc
	v_cmp_gt_f32_e32 vcc, 0, v157
	v_pk_mul_f32 v[156:157], v[158:159], v[158:159]
	s_nop 0
	v_cndmask_b32_e32 v182, v151, v153, vcc
	v_pk_fma_f32 v[150:151], v[174:175], s[98:99], v[144:145] op_sel_hi:[1,0,0]
	v_pk_mul_f32 v[152:153], v[172:173], v[172:173]
	v_pk_fma_f32 v[150:151], v[174:175], v[150:151], s[90:91] op_sel_hi:[1,1,0]
	v_pk_mul_f32 v[152:153], v[152:153], s[74:75] op_sel_hi:[1,0]
	v_pk_fma_f32 v[150:151], v[174:175], v[150:151], s[4:5] op_sel_hi:[1,1,0]
	v_exp_f32_e32 v152, v152
	v_exp_f32_e32 v153, v153
	v_pk_fma_f32 v[150:151], v[174:175], v[150:151], s[78:79] op_sel_hi:[1,1,0]
	v_cmp_gt_f32_e32 vcc, 0, v172
	v_pk_mul_f32 v[150:151], v[174:175], v[150:151]
	v_and_b32_e32 v175, 0x7fffffff, v159
	v_and_b32_e32 v174, 0x7fffffff, v158
	v_pk_fma_f32 v[174:175], v[174:175], s[96:97], 1.0 op_sel_hi:[1,0,0]
	v_pk_mul_f32 v[150:151], v[152:153], v[150:151]
	v_rcp_f32_e32 v174, v174
	v_rcp_f32_e32 v175, v175
	v_pk_mul_f32 v[152:153], v[172:173], v[150:151]
	v_pk_fma_f32 v[150:151], v[172:173], v[150:151], v[172:173] neg_lo:[1,0,0] neg_hi:[1,0,0]
	s_nop 0
	v_cndmask_b32_e32 v172, v150, v152, vcc
	v_cmp_gt_f32_e32 vcc, 0, v173
	s_nop 1
	v_cndmask_b32_e32 v173, v151, v153, vcc
	v_pk_fma_f32 v[150:151], v[174:175], s[98:99], v[144:145] op_sel_hi:[1,0,0]
	v_pk_mul_f32 v[152:153], v[156:157], s[74:75] op_sel_hi:[1,0]
	v_pk_fma_f32 v[150:151], v[174:175], v[150:151], s[90:91] op_sel_hi:[1,1,0]
	v_exp_f32_e32 v152, v152
	v_exp_f32_e32 v153, v153
	v_pk_fma_f32 v[150:151], v[174:175], v[150:151], s[4:5] op_sel_hi:[1,1,0]
	v_cmp_gt_f32_e32 vcc, 0, v158
	v_pk_fma_f32 v[150:151], v[174:175], v[150:151], s[78:79] op_sel_hi:[1,1,0]
	s_nop 0
	v_pk_mul_f32 v[150:151], v[174:175], v[150:151]
	s_nop 0
	v_pk_mul_f32 v[150:151], v[152:153], v[150:151]
	s_nop 0
	v_pk_mul_f32 v[152:153], v[158:159], v[150:151]
	v_pk_fma_f32 v[150:151], v[158:159], v[150:151], v[158:159] neg_lo:[1,0,0] neg_hi:[1,0,0]
	s_nop 0
	v_cndmask_b32_e32 v156, v150, v152, vcc
	v_cmp_gt_f32_e32 vcc, 0, v159
	v_cvt_pk_bf16_f32 v150, v155, v180
	v_pk_fma_f32 v[158:159], v[98:99], v[154:155], v[130:131] op_sel_hi:[1,0,1]
	s_nop 0
	v_cndmask_b32_e32 v153, v151, v153, vcc
	v_cvt_pk_bf16_f32 v151, v181, v182
	v_cvt_pk_bf16_f32 v152, v172, v173
	v_cvt_pk_bf16_f32 v153, v156, v153
	global_store_dwordx4 v[148:149], v[150:153], off
	v_pk_fma_f32 v[156:157], v[102:103], v[154:155], v[134:135] op_sel_hi:[1,0,1]
	s_nop 0
	v_pk_fma_f32 v[150:151], v[100:101], v[154:155], v[132:133] op_sel_hi:[1,0,1]
	v_and_b32_e32 v181, 0x7fffffff, v157
	v_and_b32_e32 v153, 0x7fffffff, v151
	v_and_b32_e32 v152, 0x7fffffff, v150
	v_pk_fma_f32 v[152:153], v[152:153], s[96:97], 1.0 op_sel_hi:[1,0,0]
	v_pk_mul_f32 v[174:175], v[150:151], v[150:151]
	v_rcp_f32_e32 v152, v152
	v_rcp_f32_e32 v153, v153
	v_pk_mul_f32 v[174:175], v[174:175], s[74:75] op_sel_hi:[1,0]
	v_and_b32_e32 v180, 0x7fffffff, v156
	v_exp_f32_e32 v174, v174
; __device__ __forceinline__ unsigned cvt_pk_bf16(float lo, float hi) { unsigned r; asm volatile("v_cvt_pk_bf16_f32 %0, %1, %2" : "=v"(r) : "v"(lo), "v"(hi)); return r; }
; __device__ __forceinline__ f32x2 gelu_pk(f32x2 v) {
;     const f32x2 av = __builtin_elementwise_abs(v), d = av * 0.2316418882f + 1.0f;
;     f32x2 t; t.x = __builtin_amdgcn_rcpf(d.x); t.y = __builtin_amdgcn_rcpf(d.y);
;     f32x2 q = t * 0.5307027145f + (-0.7265760135f); q = q * t + 0.7107068705f; q = q * t + (-0.142248368f); q = q * t + 0.127414796f; q = q * t;
;     const f32x2 s = (v * v) * (-0.72134752044f);
;     f32x2 e; e.x = __builtin_amdgcn_exp2f(s.x); e.y = __builtin_amdgcn_exp2f(s.y);
;     const f32x2 m = v * (q * e), r = v - m;
;     f32x2 o; o.x = v.x < 0.f ? m.x : r.x; o.y = v.y < 0.f ? m.y : r.y; return o;
; }
;     static __device__ __forceinline__ void run(const f32x4 (&acc)[2][2][4][2], const Unit& u, int wr, int wc, int fr, int fq, bf16_t* O, int ldc, const float* ssqA, const float* bvec) {
;     ...
;             for (int m = 0; m < 4; ++m) { const int row = row0 + ai * HALF + m * 16; const float r = row_scale(ssqA, nullptr, row); bf16_t* rowp = O + ((unsigned)row * (unsigned)ldc + (unsigned)col0);
; #pragma unroll
;                 for (int bj = 0; bj < 2; ++bj) { const f32x4 v0 = acc[ai][bj][m][0] * r + bv[bj][0], v1 = acc[ai][bj][m][1] * r + bv[bj][1];
;                     const f32x2 a = gelu_pk((f32x2){v0[0], v0[1]}), b2 = gelu_pk((f32x2){v0[2], v0[3]}), c = gelu_pk((f32x2){v1[0], v1[1]}), d = gelu_pk((f32x2){v1[2], v1[3]});
;                     u32x4 w; w.x = cvt_pk_bf16(a.x, a.y); w.y = cvt_pk_bf16(b2.x, b2.y); w.z = cvt_pk_bf16(c.x, c.y); w.w = cvt_pk_bf16(d.x, d.y);
;                     *(u32x4*)(rowp + bj * HALF) = w; }
	v_pk_fma_f32 v[172:173], v[152:153], s[98:99], v[144:145] op_sel_hi:[1,0,0]
	v_exp_f32_e32 v175, v175
	v_pk_fma_f32 v[172:173], v[152:153], v[172:173], s[90:91] op_sel_hi:[1,1,0]
	v_pk_fma_f32 v[180:181], v[180:181], s[96:97], 1.0 op_sel_hi:[1,0,0]
	v_pk_fma_f32 v[172:173], v[152:153], v[172:173], s[4:5] op_sel_hi:[1,1,0]
	v_rcp_f32_e32 v180, v180
	v_pk_fma_f32 v[172:173], v[152:153], v[172:173], s[78:79] op_sel_hi:[1,1,0]
	v_rcp_f32_e32 v181, v181
	v_pk_mul_f32 v[152:153], v[152:153], v[172:173]
	v_cmp_gt_f32_e32 vcc, 0, v150
	v_pk_mul_f32 v[152:153], v[174:175], v[152:153]
	v_pk_mul_f32 v[172:173], v[156:157], v[156:157]
	v_pk_mul_f32 v[174:175], v[150:151], v[152:153]
	v_pk_fma_f32 v[152:153], v[150:151], v[152:153], v[150:151] neg_lo:[1,0,0] neg_hi:[1,0,0]
	v_pk_fma_f32 v[154:155], v[96:97], v[154:155], v[128:129] op_sel_hi:[1,0,1]
	v_cndmask_b32_e32 v174, v152, v174, vcc
	v_cmp_gt_f32_e32 vcc, 0, v151
	v_pk_fma_f32 v[150:151], v[180:181], s[98:99], v[144:145] op_sel_hi:[1,0,0]
	s_nop 0
	v_cndmask_b32_e32 v175, v153, v175, vcc
	v_pk_mul_f32 v[152:153], v[172:173], s[74:75] op_sel_hi:[1,0]
	v_pk_fma_f32 v[150:151], v[180:181], v[150:151], s[90:91] op_sel_hi:[1,1,0]
	v_exp_f32_e32 v152, v152
	v_exp_f32_e32 v153, v153
	v_pk_fma_f32 v[150:151], v[180:181], v[150:151], s[4:5] op_sel_hi:[1,1,0]
	v_and_b32_e32 v173, 0x7fffffff, v155
	v_and_b32_e32 v172, 0x7fffffff, v154
	v_pk_fma_f32 v[150:151], v[180:181], v[150:151], s[78:79] op_sel_hi:[1,1,0]
	v_pk_fma_f32 v[172:173], v[172:173], s[96:97], 1.0 op_sel_hi:[1,0,0]
	v_pk_mul_f32 v[150:151], v[180:181], v[150:151]
	v_rcp_f32_e32 v172, v172
	v_rcp_f32_e32 v173, v173
	v_pk_mul_f32 v[150:151], v[152:153], v[150:151]
	v_cmp_gt_f32_e32 vcc, 0, v156
	v_pk_mul_f32 v[152:153], v[156:157], v[150:151]
	v_pk_fma_f32 v[150:151], v[156:157], v[150:151], v[156:157] neg_lo:[1,0,0] neg_hi:[1,0,0]
	s_nop 0
	v_cndmask_b32_e32 v180, v150, v152, vcc
	v_cmp_gt_f32_e32 vcc, 0, v157
	v_pk_mul_f32 v[156:157], v[158:159], v[158:159]
	s_nop 0
	v_cndmask_b32_e32 v181, v151, v153, vcc
	v_pk_fma_f32 v[150:151], v[172:173], s[98:99], v[144:145] op_sel_hi:[1,0,0]
	v_pk_mul_f32 v[152:153], v[154:155], v[154:155]
	v_pk_fma_f32 v[150:151], v[172:173], v[150:151], s[90:91] op_sel_hi:[1,1,0]
	v_pk_mul_f32 v[152:153], v[152:153], s[74:75] op_sel_hi:[1,0]
	v_pk_fma_f32 v[150:151], v[172:173], v[150:151], s[4:5] op_sel_hi:[1,1,0]
	v_exp_f32_e32 v152, v152
	v_exp_f32_e32 v153, v153
	v_pk_fma_f32 v[150:151], v[172:173], v[150:151], s[78:79] op_sel_hi:[1,1,0]
	v_cmp_gt_f32_e32 vcc, 0, v154
	v_pk_mul_f32 v[150:151], v[172:173], v[150:151]
	v_and_b32_e32 v173, 0x7fffffff, v159
	v_and_b32_e32 v172, 0x7fffffff, v158
	v_pk_fma_f32 v[172:173], v[172:173], s[96:97], 1.0 op_sel_hi:[1,0,0]
	v_pk_mul_f32 v[150:151], v[152:153], v[150:151]
	v_rcp_f32_e32 v172, v172
	v_rcp_f32_e32 v173, v173
	v_pk_mul_f32 v[152:153], v[154:155], v[150:151]
	v_pk_fma_f32 v[150:151], v[154:155], v[150:151], v[154:155] neg_lo:[1,0,0] neg_hi:[1,0,0]
	s_nop 0
	v_cndmask_b32_e32 v154, v150, v152, vcc
	v_cmp_gt_f32_e32 vcc, 0, v155
	s_nop 1
	v_cndmask_b32_e32 v155, v151, v153, vcc
	v_pk_fma_f32 v[150:151], v[172:173], s[98:99], v[144:145] op_sel_hi:[1,0,0]
	v_pk_mul_f32 v[152:153], v[156:157], s[74:75] op_sel_hi:[1,0]
	v_pk_fma_f32 v[150:151], v[172:173], v[150:151], s[90:91] op_sel_hi:[1,1,0]
	v_exp_f32_e32 v152, v152
	v_exp_f32_e32 v153, v153
	v_pk_fma_f32 v[150:151], v[172:173], v[150:151], s[4:5] op_sel_hi:[1,1,0]
	v_cmp_gt_f32_e32 vcc, 0, v158
	v_pk_fma_f32 v[150:151], v[172:173], v[150:151], s[78:79] op_sel_hi:[1,1,0]
	s_nop 0
	v_pk_mul_f32 v[150:151], v[172:173], v[150:151]
	s_nop 0
	v_pk_mul_f32 v[150:151], v[152:153], v[150:151]
	s_nop 0
	v_pk_mul_f32 v[152:153], v[158:159], v[150:151]
	v_pk_fma_f32 v[150:151], v[158:159], v[150:151], v[158:159] neg_lo:[1,0,0] neg_hi:[1,0,0]
	s_nop 0
	v_cndmask_b32_e32 v156, v150, v152, vcc
	v_cmp_gt_f32_e32 vcc, 0, v159
	v_cvt_pk_bf16_f32 v150, v174, v175
	s_nop 1
	v_cndmask_b32_e32 v153, v151, v153, vcc
	v_cvt_pk_bf16_f32 v151, v180, v181
	v_cvt_pk_bf16_f32 v152, v154, v155
	v_cvt_pk_bf16_f32 v153, v156, v153
	global_store_dwordx4 v[148:149], v[150:153], off offset:256
	s_nop 0
	s_waitcnt vmcnt(11)
	v_fmamk_f32 v148, v199, 0x3a800000, v222
	v_rsq_f32_e32 v154, v148
	v_lshl_add_u64 v[148:149], v[176:177], 1, s[2:3]
	v_add_u32_e32 v176, s8, v176
	v_pk_fma_f32 v[150:151], v[92:93], v[154:155], v[140:141] op_sel_hi:[1,0,1]
	s_nop 0
	v_and_b32_e32 v153, 0x7fffffff, v151
	v_and_b32_e32 v152, 0x7fffffff, v150
	v_pk_fma_f32 v[152:153], v[152:153], s[96:97], 1.0 op_sel_hi:[1,0,0]
	v_pk_mul_f32 v[180:181], v[150:151], v[150:151]
	v_rcp_f32_e32 v152, v152
	v_rcp_f32_e32 v153, v153
	v_pk_mul_f32 v[180:181], v[180:181], s[74:75] op_sel_hi:[1,0]
	v_pk_fma_f32 v[156:157], v[94:95], v[154:155], v[142:143] op_sel_hi:[1,0,1]
	v_exp_f32_e32 v180, v180
	v_pk_fma_f32 v[174:175], v[152:153], s[98:99], v[144:145] op_sel_hi:[1,0,0]
	v_exp_f32_e32 v181, v181
	v_pk_fma_f32 v[174:175], v[152:153], v[174:175], s[90:91] op_sel_hi:[1,1,0]
	v_and_b32_e32 v183, 0x7fffffff, v157
	v_pk_fma_f32 v[174:175], v[152:153], v[174:175], s[4:5] op_sel_hi:[1,1,0]
	v_and_b32_e32 v182, 0x7fffffff, v156
	v_pk_fma_f32 v[174:175], v[152:153], v[174:175], s[78:79] op_sel_hi:[1,1,0]
	v_pk_fma_f32 v[182:183], v[182:183], s[96:97], 1.0 op_sel_hi:[1,0,0]
	v_pk_mul_f32 v[152:153], v[152:153], v[174:175]
	v_rcp_f32_e32 v182, v182
	v_rcp_f32_e32 v183, v183
	v_pk_mul_f32 v[152:153], v[180:181], v[152:153]
	v_cmp_gt_f32_e32 vcc, 0, v150
	v_pk_mul_f32 v[180:181], v[150:151], v[152:153]
	v_pk_fma_f32 v[152:153], v[150:151], v[152:153], v[150:151] neg_lo:[1,0,0] neg_hi:[1,0,0]
; __device__ __forceinline__ unsigned cvt_pk_bf16(float lo, float hi) { unsigned r; asm volatile("v_cvt_pk_bf16_f32 %0, %1, %2" : "=v"(r) : "v"(lo), "v"(hi)); return r; }
; __device__ __forceinline__ f32x2 gelu_pk(f32x2 v) {
;     const f32x2 av = __builtin_elementwise_abs(v), d = av * 0.2316418882f + 1.0f;
;     f32x2 t; t.x = __builtin_amdgcn_rcpf(d.x); t.y = __builtin_amdgcn_rcpf(d.y);
;     f32x2 q = t * 0.5307027145f + (-0.7265760135f); q = q * t + 0.7107068705f; q = q * t + (-0.142248368f); q = q * t + 0.127414796f; q = q * t;
;     const f32x2 s = (v * v) * (-0.72134752044f);
;     f32x2 e; e.x = __builtin_amdgcn_exp2f(s.x); e.y = __builtin_amdgcn_exp2f(s.y);
;     const f32x2 m = v * (q * e), r = v - m;
;     f32x2 o; o.x = v.x < 0.f ? m.x : r.x; o.y = v.y < 0.f ? m.y : r.y; return o;
; }
;     static __device__ __forceinline__ void run(const f32x4 (&acc)[2][2][4][2], const Unit& u, int wr, int wc, int fr, int fq, bf16_t* O, int ldc, const float* ssqA, const float* bvec) {
;     ...
;             for (int m = 0; m < 4; ++m) { const int row = row0 + ai * HALF + m * 16; const float r = row_scale(ssqA, nullptr, row); bf16_t* rowp = O + ((unsigned)row * (unsigned)ldc + (unsigned)col0);
; #pragma unroll
;                 for (int bj = 0; bj < 2; ++bj) { const f32x4 v0 = acc[ai][bj][m][0] * r + bv[bj][0], v1 = acc[ai][bj][m][1] * r + bv[bj][1];
;                     const f32x2 a = gelu_pk((f32x2){v0[0], v0[1]}), b2 = gelu_pk((f32x2){v0[2], v0[3]}), c = gelu_pk((f32x2){v1[0], v1[1]}), d = gelu_pk((f32x2){v1[2], v1[3]});
;                     u32x4 w; w.x = cvt_pk_bf16(a.x, a.y); w.y = cvt_pk_bf16(b2.x, b2.y); w.z = cvt_pk_bf16(c.x, c.y); w.w = cvt_pk_bf16(d.x, d.y);
;                     *(u32x4*)(rowp + bj * HALF) = w; }
	v_pk_fma_f32 v[158:159], v[90:91], v[154:155], v[138:139] op_sel_hi:[1,0,1]
	v_pk_fma_f32 v[172:173], v[88:89], v[154:155], v[136:137] op_sel_hi:[1,0,1]
	v_pk_mul_f32 v[174:175], v[156:157], v[156:157]
	v_cndmask_b32_e32 v155, v152, v180, vcc
	v_cmp_gt_f32_e32 vcc, 0, v151
	v_pk_fma_f32 v[150:151], v[182:183], s[98:99], v[144:145] op_sel_hi:[1,0,0]
	s_nop 0
	v_cndmask_b32_e32 v180, v153, v181, vcc
	v_pk_mul_f32 v[152:153], v[174:175], s[74:75] op_sel_hi:[1,0]
	v_pk_fma_f32 v[150:151], v[182:183], v[150:151], s[90:91] op_sel_hi:[1,1,0]
	v_exp_f32_e32 v152, v152
	v_exp_f32_e32 v153, v153
	v_pk_fma_f32 v[150:151], v[182:183], v[150:151], s[4:5] op_sel_hi:[1,1,0]
	v_and_b32_e32 v175, 0x7fffffff, v173
	v_and_b32_e32 v174, 0x7fffffff, v172
	v_pk_fma_f32 v[150:151], v[182:183], v[150:151], s[78:79] op_sel_hi:[1,1,0]
	v_pk_fma_f32 v[174:175], v[174:175], s[96:97], 1.0 op_sel_hi:[1,0,0]
	v_pk_mul_f32 v[150:151], v[182:183], v[150:151]
	v_rcp_f32_e32 v174, v174
	v_rcp_f32_e32 v175, v175
	v_pk_mul_f32 v[150:151], v[152:153], v[150:151]
	v_cmp_gt_f32_e32 vcc, 0, v156
	v_pk_mul_f32 v[152:153], v[156:157], v[150:151]
	v_pk_fma_f32 v[150:151], v[156:157], v[150:151], v[156:157] neg_lo:[1,0,0] neg_hi:[1,0,0]
	s_nop 0
	v_cndmask_b32_e32 v181, v150, v152, vcc
	v_cmp_gt_f32_e32 vcc, 0, v157
	v_pk_mul_f32 v[156:157], v[158:159], v[158:159]
	s_nop 0
	v_cndmask_b32_e32 v182, v151, v153, vcc
	v_pk_fma_f32 v[150:151], v[174:175], s[98:99], v[144:145] op_sel_hi:[1,0,0]
	v_pk_mul_f32 v[152:153], v[172:173], v[172:173]
	v_pk_fma_f32 v[150:151], v[174:175], v[150:151], s[90:91] op_sel_hi:[1,1,0]
	v_pk_mul_f32 v[152:153], v[152:153], s[74:75] op_sel_hi:[1,0]
	v_pk_fma_f32 v[150:151], v[174:175], v[150:151], s[4:5] op_sel_hi:[1,1,0]
	v_exp_f32_e32 v152, v152
	v_exp_f32_e32 v153, v153
	v_pk_fma_f32 v[150:151], v[174:175], v[150:151], s[78:79] op_sel_hi:[1,1,0]
	v_cmp_gt_f32_e32 vcc, 0, v172
	v_pk_mul_f32 v[150:151], v[174:175], v[150:151]
	v_and_b32_e32 v175, 0x7fffffff, v159
	v_and_b32_e32 v174, 0x7fffffff, v158
	v_pk_fma_f32 v[174:175], v[174:175], s[96:97], 1.0 op_sel_hi:[1,0,0]
	v_pk_mul_f32 v[150:151], v[152:153], v[150:151]
	v_rcp_f32_e32 v174, v174
	v_rcp_f32_e32 v175, v175
	v_pk_mul_f32 v[152:153], v[172:173], v[150:151]
	v_pk_fma_f32 v[150:151], v[172:173], v[150:151], v[172:173] neg_lo:[1,0,0] neg_hi:[1,0,0]
	s_nop 0
	v_cndmask_b32_e32 v172, v150, v152, vcc
	v_cmp_gt_f32_e32 vcc, 0, v173
	s_nop 1
	v_cndmask_b32_e32 v173, v151, v153, vcc
	v_pk_fma_f32 v[150:151], v[174:175], s[98:99], v[144:145] op_sel_hi:[1,0,0]
	v_pk_mul_f32 v[152:153], v[156:157], s[74:75] op_sel_hi:[1,0]
	v_pk_fma_f32 v[150:151], v[174:175], v[150:151], s[90:91] op_sel_hi:[1,1,0]
	v_exp_f32_e32 v152, v152
	v_exp_f32_e32 v153, v153
	v_pk_fma_f32 v[150:151], v[174:175], v[150:151], s[4:5] op_sel_hi:[1,1,0]
	v_cmp_gt_f32_e32 vcc, 0, v158
	v_pk_fma_f32 v[150:151], v[174:175], v[150:151], s[78:79] op_sel_hi:[1,1,0]
	s_nop 0
	v_pk_mul_f32 v[150:151], v[174:175], v[150:151]
	s_nop 0
	v_pk_mul_f32 v[150:151], v[152:153], v[150:151]
	s_nop 0
	v_pk_mul_f32 v[152:153], v[158:159], v[150:151]
	v_pk_fma_f32 v[150:151], v[158:159], v[150:151], v[158:159] neg_lo:[1,0,0] neg_hi:[1,0,0]
	s_nop 0
	v_cndmask_b32_e32 v156, v150, v152, vcc
	v_cmp_gt_f32_e32 vcc, 0, v159
	v_cvt_pk_bf16_f32 v150, v155, v180
	v_pk_fma_f32 v[158:159], v[82:83], v[154:155], v[130:131] op_sel_hi:[1,0,1]
	s_nop 0
	v_cndmask_b32_e32 v153, v151, v153, vcc
	v_cvt_pk_bf16_f32 v151, v181, v182
	v_cvt_pk_bf16_f32 v152, v172, v173
	v_cvt_pk_bf16_f32 v153, v156, v153
	global_store_dwordx4 v[148:149], v[150:153], off
	v_pk_fma_f32 v[156:157], v[86:87], v[154:155], v[134:135] op_sel_hi:[1,0,1]
	s_nop 0
	v_pk_fma_f32 v[150:151], v[84:85], v[154:155], v[132:133] op_sel_hi:[1,0,1]
	v_and_b32_e32 v181, 0x7fffffff, v157
	v_and_b32_e32 v153, 0x7fffffff, v151
	v_and_b32_e32 v152, 0x7fffffff, v150
	v_pk_fma_f32 v[152:153], v[152:153], s[96:97], 1.0 op_sel_hi:[1,0,0]
	v_pk_mul_f32 v[174:175], v[150:151], v[150:151]
	v_rcp_f32_e32 v152, v152
	v_rcp_f32_e32 v153, v153
	v_pk_mul_f32 v[174:175], v[174:175], s[74:75] op_sel_hi:[1,0]
	v_and_b32_e32 v180, 0x7fffffff, v156
	v_exp_f32_e32 v174, v174
	v_pk_fma_f32 v[172:173], v[152:153], s[98:99], v[144:145] op_sel_hi:[1,0,0]
	v_exp_f32_e32 v175, v175
	v_pk_fma_f32 v[172:173], v[152:153], v[172:173], s[90:91] op_sel_hi:[1,1,0]
	v_pk_fma_f32 v[180:181], v[180:181], s[96:97], 1.0 op_sel_hi:[1,0,0]
	v_pk_fma_f32 v[172:173], v[152:153], v[172:173], s[4:5] op_sel_hi:[1,1,0]
	v_rcp_f32_e32 v180, v180
	v_pk_fma_f32 v[172:173], v[152:153], v[172:173], s[78:79] op_sel_hi:[1,1,0]
	v_rcp_f32_e32 v181, v181
	v_pk_mul_f32 v[152:153], v[152:153], v[172:173]
	v_cmp_gt_f32_e32 vcc, 0, v150
	v_pk_mul_f32 v[152:153], v[174:175], v[152:153]
	v_pk_mul_f32 v[172:173], v[156:157], v[156:157]
	v_pk_mul_f32 v[174:175], v[150:151], v[152:153]
	v_pk_fma_f32 v[152:153], v[150:151], v[152:153], v[150:151] neg_lo:[1,0,0] neg_hi:[1,0,0]
	v_pk_fma_f32 v[154:155], v[80:81], v[154:155], v[128:129] op_sel_hi:[1,0,1]
	v_cndmask_b32_e32 v174, v152, v174, vcc
	v_cmp_gt_f32_e32 vcc, 0, v151
	v_pk_fma_f32 v[150:151], v[180:181], s[98:99], v[144:145] op_sel_hi:[1,0,0]
	s_nop 0
	v_cndmask_b32_e32 v175, v153, v175, vcc
	v_pk_mul_f32 v[152:153], v[172:173], s[74:75] op_sel_hi:[1,0]
	v_pk_fma_f32 v[150:151], v[180:181], v[150:151], s[90:91] op_sel_hi:[1,1,0]
	v_exp_f32_e32 v152, v152
	v_exp_f32_e32 v153, v153
	v_pk_fma_f32 v[150:151], v[180:181], v[150:151], s[4:5] op_sel_hi:[1,1,0]
	v_and_b32_e32 v173, 0x7fffffff, v155
	v_and_b32_e32 v172, 0x7fffffff, v154
	v_pk_fma_f32 v[150:151], v[180:181], v[150:151], s[78:79] op_sel_hi:[1,1,0]
; __device__ __forceinline__ unsigned cvt_pk_bf16(float lo, float hi) { unsigned r; asm volatile("v_cvt_pk_bf16_f32 %0, %1, %2" : "=v"(r) : "v"(lo), "v"(hi)); return r; }
; __device__ __forceinline__ f32x2 gelu_pk(f32x2 v) {
;     const f32x2 av = __builtin_elementwise_abs(v), d = av * 0.2316418882f + 1.0f;
;     f32x2 t; t.x = __builtin_amdgcn_rcpf(d.x); t.y = __builtin_amdgcn_rcpf(d.y);
;     f32x2 q = t * 0.5307027145f + (-0.7265760135f); q = q * t + 0.7107068705f; q = q * t + (-0.142248368f); q = q * t + 0.127414796f; q = q * t;
;     const f32x2 s = (v * v) * (-0.72134752044f);
;     f32x2 e; e.x = __builtin_amdgcn_exp2f(s.x); e.y = __builtin_amdgcn_exp2f(s.y);
;     const f32x2 m = v * (q * e), r = v - m;
;     f32x2 o; o.x = v.x < 0.f ? m.x : r.x; o.y = v.y < 0.f ? m.y : r.y; return o;
; }
;     static __device__ __forceinline__ void run(const f32x4 (&acc)[2][2][4][2], const Unit& u, int wr, int wc, int fr, int fq, bf16_t* O, int ldc, const float* ssqA, const float* bvec) {
;     ...
;             for (int m = 0; m < 4; ++m) { const int row = row0 + ai * HALF + m * 16; const float r = row_scale(ssqA, nullptr, row); bf16_t* rowp = O + ((unsigned)row * (unsigned)ldc + (unsigned)col0);
; #pragma unroll
;                 for (int bj = 0; bj < 2; ++bj) { const f32x4 v0 = acc[ai][bj][m][0] * r + bv[bj][0], v1 = acc[ai][bj][m][1] * r + bv[bj][1];
;                     const f32x2 a = gelu_pk((f32x2){v0[0], v0[1]}), b2 = gelu_pk((f32x2){v0[2], v0[3]}), c = gelu_pk((f32x2){v1[0], v1[1]}), d = gelu_pk((f32x2){v1[2], v1[3]});
;                     u32x4 w; w.x = cvt_pk_bf16(a.x, a.y); w.y = cvt_pk_bf16(b2.x, b2.y); w.z = cvt_pk_bf16(c.x, c.y); w.w = cvt_pk_bf16(d.x, d.y);
;                     *(u32x4*)(rowp + bj * HALF) = w; }
	v_pk_fma_f32 v[172:173], v[172:173], s[96:97], 1.0 op_sel_hi:[1,0,0]
	v_pk_mul_f32 v[150:151], v[180:181], v[150:151]
	v_rcp_f32_e32 v172, v172
	v_rcp_f32_e32 v173, v173
	v_pk_mul_f32 v[150:151], v[152:153], v[150:151]
	v_cmp_gt_f32_e32 vcc, 0, v156
	v_pk_mul_f32 v[152:153], v[156:157], v[150:151]
	v_pk_fma_f32 v[150:151], v[156:157], v[150:151], v[156:157] neg_lo:[1,0,0] neg_hi:[1,0,0]
	s_nop 0
	v_cndmask_b32_e32 v180, v150, v152, vcc
	v_cmp_gt_f32_e32 vcc, 0, v157
	v_pk_mul_f32 v[156:157], v[158:159], v[158:159]
	s_nop 0
	v_cndmask_b32_e32 v181, v151, v153, vcc
	v_pk_fma_f32 v[150:151], v[172:173], s[98:99], v[144:145] op_sel_hi:[1,0,0]
	v_pk_mul_f32 v[152:153], v[154:155], v[154:155]
	v_pk_fma_f32 v[150:151], v[172:173], v[150:151], s[90:91] op_sel_hi:[1,1,0]
	v_pk_mul_f32 v[152:153], v[152:153], s[74:75] op_sel_hi:[1,0]
	v_pk_fma_f32 v[150:151], v[172:173], v[150:151], s[4:5] op_sel_hi:[1,1,0]
	v_exp_f32_e32 v152, v152
	v_exp_f32_e32 v153, v153
	v_pk_fma_f32 v[150:151], v[172:173], v[150:151], s[78:79] op_sel_hi:[1,1,0]
	v_cmp_gt_f32_e32 vcc, 0, v154
	v_pk_mul_f32 v[150:151], v[172:173], v[150:151]
	v_and_b32_e32 v173, 0x7fffffff, v159
	v_and_b32_e32 v172, 0x7fffffff, v158
	v_pk_fma_f32 v[172:173], v[172:173], s[96:97], 1.0 op_sel_hi:[1,0,0]
	v_pk_mul_f32 v[150:151], v[152:153], v[150:151]
	v_rcp_f32_e32 v172, v172
	v_rcp_f32_e32 v173, v173
	v_pk_mul_f32 v[152:153], v[154:155], v[150:151]
	v_pk_fma_f32 v[150:151], v[154:155], v[150:151], v[154:155] neg_lo:[1,0,0] neg_hi:[1,0,0]
	s_nop 0
	v_cndmask_b32_e32 v154, v150, v152, vcc
	v_cmp_gt_f32_e32 vcc, 0, v155
	s_nop 1
	v_cndmask_b32_e32 v155, v151, v153, vcc
	v_pk_fma_f32 v[150:151], v[172:173], s[98:99], v[144:145] op_sel_hi:[1,0,0]
	v_pk_mul_f32 v[152:153], v[156:157], s[74:75] op_sel_hi:[1,0]
	v_pk_fma_f32 v[150:151], v[172:173], v[150:151], s[90:91] op_sel_hi:[1,1,0]
	v_exp_f32_e32 v152, v152
	v_exp_f32_e32 v153, v153
	v_pk_fma_f32 v[150:151], v[172:173], v[150:151], s[4:5] op_sel_hi:[1,1,0]
	v_cmp_gt_f32_e32 vcc, 0, v158
	v_pk_fma_f32 v[150:151], v[172:173], v[150:151], s[78:79] op_sel_hi:[1,1,0]
	s_nop 0
	v_pk_mul_f32 v[150:151], v[172:173], v[150:151]
	s_nop 0
	v_pk_mul_f32 v[150:151], v[152:153], v[150:151]
	s_nop 0
	v_pk_mul_f32 v[152:153], v[158:159], v[150:151]
	v_pk_fma_f32 v[150:151], v[158:159], v[150:151], v[158:159] neg_lo:[1,0,0] neg_hi:[1,0,0]
	s_nop 0
	v_cndmask_b32_e32 v156, v150, v152, vcc
	v_cmp_gt_f32_e32 vcc, 0, v159
	v_cvt_pk_bf16_f32 v150, v174, v175
	s_nop 1
	v_cndmask_b32_e32 v153, v151, v153, vcc
	v_cvt_pk_bf16_f32 v151, v180, v181
	v_cvt_pk_bf16_f32 v152, v154, v155
	v_cvt_pk_bf16_f32 v153, v156, v153
	global_store_dwordx4 v[148:149], v[150:153], off offset:256
	s_nop 0
	s_waitcnt vmcnt(12)
	v_fmamk_f32 v148, v200, 0x3a800000, v222
	v_rsq_f32_e32 v154, v148
	v_lshl_add_u64 v[148:149], v[176:177], 1, s[2:3]
	v_add_u32_e32 v176, s9, v176
	v_pk_fma_f32 v[150:151], v[76:77], v[154:155], v[140:141] op_sel_hi:[1,0,1]
	s_nop 0
	v_and_b32_e32 v153, 0x7fffffff, v151
	v_and_b32_e32 v152, 0x7fffffff, v150
	v_pk_fma_f32 v[152:153], v[152:153], s[96:97], 1.0 op_sel_hi:[1,0,0]
	v_pk_mul_f32 v[180:181], v[150:151], v[150:151]
	v_rcp_f32_e32 v152, v152
	v_rcp_f32_e32 v153, v153
	v_pk_mul_f32 v[180:181], v[180:181], s[74:75] op_sel_hi:[1,0]
	v_pk_fma_f32 v[156:157], v[78:79], v[154:155], v[142:143] op_sel_hi:[1,0,1]
	v_exp_f32_e32 v180, v180
	v_pk_fma_f32 v[174:175], v[152:153], s[98:99], v[144:145] op_sel_hi:[1,0,0]
	v_exp_f32_e32 v181, v181
	v_pk_fma_f32 v[174:175], v[152:153], v[174:175], s[90:91] op_sel_hi:[1,1,0]
	v_and_b32_e32 v183, 0x7fffffff, v157
	v_pk_fma_f32 v[174:175], v[152:153], v[174:175], s[4:5] op_sel_hi:[1,1,0]
	v_and_b32_e32 v182, 0x7fffffff, v156
	v_pk_fma_f32 v[174:175], v[152:153], v[174:175], s[78:79] op_sel_hi:[1,1,0]
	v_pk_fma_f32 v[182:183], v[182:183], s[96:97], 1.0 op_sel_hi:[1,0,0]
	v_pk_mul_f32 v[152:153], v[152:153], v[174:175]
	v_rcp_f32_e32 v182, v182
	v_rcp_f32_e32 v183, v183
	v_pk_mul_f32 v[152:153], v[180:181], v[152:153]
	v_cmp_gt_f32_e32 vcc, 0, v150
	v_pk_mul_f32 v[180:181], v[150:151], v[152:153]
	v_pk_fma_f32 v[152:153], v[150:151], v[152:153], v[150:151] neg_lo:[1,0,0] neg_hi:[1,0,0]
	v_pk_fma_f32 v[158:159], v[74:75], v[154:155], v[138:139] op_sel_hi:[1,0,1]
	v_pk_fma_f32 v[172:173], v[72:73], v[154:155], v[136:137] op_sel_hi:[1,0,1]
	v_pk_mul_f32 v[174:175], v[156:157], v[156:157]
	v_cndmask_b32_e32 v155, v152, v180, vcc
	v_cmp_gt_f32_e32 vcc, 0, v151
	v_pk_fma_f32 v[150:151], v[182:183], s[98:99], v[144:145] op_sel_hi:[1,0,0]
	s_nop 0
	v_cndmask_b32_e32 v180, v153, v181, vcc
	v_pk_mul_f32 v[152:153], v[174:175], s[74:75] op_sel_hi:[1,0]
	v_pk_fma_f32 v[150:151], v[182:183], v[150:151], s[90:91] op_sel_hi:[1,1,0]
	v_exp_f32_e32 v152, v152
	v_exp_f32_e32 v153, v153
	v_pk_fma_f32 v[150:151], v[182:183], v[150:151], s[4:5] op_sel_hi:[1,1,0]
	v_and_b32_e32 v175, 0x7fffffff, v173
	v_and_b32_e32 v174, 0x7fffffff, v172
	v_pk_fma_f32 v[150:151], v[182:183], v[150:151], s[78:79] op_sel_hi:[1,1,0]
	v_pk_fma_f32 v[174:175], v[174:175], s[96:97], 1.0 op_sel_hi:[1,0,0]
	v_pk_mul_f32 v[150:151], v[182:183], v[150:151]
	v_rcp_f32_e32 v174, v174
	v_rcp_f32_e32 v175, v175
	v_pk_mul_f32 v[150:151], v[152:153], v[150:151]
	v_cmp_gt_f32_e32 vcc, 0, v156
	v_pk_mul_f32 v[152:153], v[156:157], v[150:151]
	v_pk_fma_f32 v[150:151], v[156:157], v[150:151], v[156:157] neg_lo:[1,0,0] neg_hi:[1,0,0]
	s_nop 0
	v_cndmask_b32_e32 v181, v150, v152, vcc
	v_cmp_gt_f32_e32 vcc, 0, v157
	v_pk_mul_f32 v[156:157], v[158:159], v[158:159]
	s_nop 0
	v_cndmask_b32_e32 v182, v151, v153, vcc
	v_pk_fma_f32 v[150:151], v[174:175], s[98:99], v[144:145] op_sel_hi:[1,0,0]
; __device__ __forceinline__ unsigned cvt_pk_bf16(float lo, float hi) { unsigned r; asm volatile("v_cvt_pk_bf16_f32 %0, %1, %2" : "=v"(r) : "v"(lo), "v"(hi)); return r; }
; __device__ __forceinline__ f32x2 gelu_pk(f32x2 v) {
;     const f32x2 av = __builtin_elementwise_abs(v), d = av * 0.2316418882f + 1.0f;
;     f32x2 t; t.x = __builtin_amdgcn_rcpf(d.x); t.y = __builtin_amdgcn_rcpf(d.y);
;     f32x2 q = t * 0.5307027145f + (-0.7265760135f); q = q * t + 0.7107068705f; q = q * t + (-0.142248368f); q = q * t + 0.127414796f; q = q * t;
;     const f32x2 s = (v * v) * (-0.72134752044f);
;     f32x2 e; e.x = __builtin_amdgcn_exp2f(s.x); e.y = __builtin_amdgcn_exp2f(s.y);
;     const f32x2 m = v * (q * e), r = v - m;
;     f32x2 o; o.x = v.x < 0.f ? m.x : r.x; o.y = v.y < 0.f ? m.y : r.y; return o;
; }
;     static __device__ __forceinline__ void run(const f32x4 (&acc)[2][2][4][2], const Unit& u, int wr, int wc, int fr, int fq, bf16_t* O, int ldc, const float* ssqA, const float* bvec) {
;     ...
;             for (int m = 0; m < 4; ++m) { const int row = row0 + ai * HALF + m * 16; const float r = row_scale(ssqA, nullptr, row); bf16_t* rowp = O + ((unsigned)row * (unsigned)ldc + (unsigned)col0);
; #pragma unroll
;                 for (int bj = 0; bj < 2; ++bj) { const f32x4 v0 = acc[ai][bj][m][0] * r + bv[bj][0], v1 = acc[ai][bj][m][1] * r + bv[bj][1];
;                     const f32x2 a = gelu_pk((f32x2){v0[0], v0[1]}), b2 = gelu_pk((f32x2){v0[2], v0[3]}), c = gelu_pk((f32x2){v1[0], v1[1]}), d = gelu_pk((f32x2){v1[2], v1[3]});
;                     u32x4 w; w.x = cvt_pk_bf16(a.x, a.y); w.y = cvt_pk_bf16(b2.x, b2.y); w.z = cvt_pk_bf16(c.x, c.y); w.w = cvt_pk_bf16(d.x, d.y);
;                     *(u32x4*)(rowp + bj * HALF) = w; }
	v_pk_mul_f32 v[152:153], v[172:173], v[172:173]
	v_pk_fma_f32 v[150:151], v[174:175], v[150:151], s[90:91] op_sel_hi:[1,1,0]
	v_pk_mul_f32 v[152:153], v[152:153], s[74:75] op_sel_hi:[1,0]
	v_pk_fma_f32 v[150:151], v[174:175], v[150:151], s[4:5] op_sel_hi:[1,1,0]
	v_exp_f32_e32 v152, v152
	v_exp_f32_e32 v153, v153
	v_pk_fma_f32 v[150:151], v[174:175], v[150:151], s[78:79] op_sel_hi:[1,1,0]
	v_cmp_gt_f32_e32 vcc, 0, v172
	v_pk_mul_f32 v[150:151], v[174:175], v[150:151]
	v_and_b32_e32 v175, 0x7fffffff, v159
	v_and_b32_e32 v174, 0x7fffffff, v158
	v_pk_fma_f32 v[174:175], v[174:175], s[96:97], 1.0 op_sel_hi:[1,0,0]
	v_pk_mul_f32 v[150:151], v[152:153], v[150:151]
	v_rcp_f32_e32 v174, v174
	v_rcp_f32_e32 v175, v175
	v_pk_mul_f32 v[152:153], v[172:173], v[150:151]
	v_pk_fma_f32 v[150:151], v[172:173], v[150:151], v[172:173] neg_lo:[1,0,0] neg_hi:[1,0,0]
	s_nop 0
	v_cndmask_b32_e32 v172, v150, v152, vcc
	v_cmp_gt_f32_e32 vcc, 0, v173
	s_nop 1
	v_cndmask_b32_e32 v173, v151, v153, vcc
	v_pk_fma_f32 v[150:151], v[174:175], s[98:99], v[144:145] op_sel_hi:[1,0,0]
	v_pk_mul_f32 v[152:153], v[156:157], s[74:75] op_sel_hi:[1,0]
	v_pk_fma_f32 v[150:151], v[174:175], v[150:151], s[90:91] op_sel_hi:[1,1,0]
	v_exp_f32_e32 v152, v152
	v_exp_f32_e32 v153, v153
	v_pk_fma_f32 v[150:151], v[174:175], v[150:151], s[4:5] op_sel_hi:[1,1,0]
	v_cmp_gt_f32_e32 vcc, 0, v158
	v_pk_fma_f32 v[150:151], v[174:175], v[150:151], s[78:79] op_sel_hi:[1,1,0]
	s_nop 0
	v_pk_mul_f32 v[150:151], v[174:175], v[150:151]
	s_nop 0
	v_pk_mul_f32 v[150:151], v[152:153], v[150:151]
	s_nop 0
	v_pk_mul_f32 v[152:153], v[158:159], v[150:151]
	v_pk_fma_f32 v[150:151], v[158:159], v[150:151], v[158:159] neg_lo:[1,0,0] neg_hi:[1,0,0]
	s_nop 0
	v_cndmask_b32_e32 v156, v150, v152, vcc
	v_cmp_gt_f32_e32 vcc, 0, v159
	v_cvt_pk_bf16_f32 v150, v155, v180
	v_pk_fma_f32 v[158:159], v[66:67], v[154:155], v[130:131] op_sel_hi:[1,0,1]
	s_nop 0
	v_cndmask_b32_e32 v153, v151, v153, vcc
	v_cvt_pk_bf16_f32 v151, v181, v182
	v_cvt_pk_bf16_f32 v152, v172, v173
	v_cvt_pk_bf16_f32 v153, v156, v153
	global_store_dwordx4 v[148:149], v[150:153], off
	v_pk_fma_f32 v[156:157], v[70:71], v[154:155], v[134:135] op_sel_hi:[1,0,1]
	s_nop 0
	v_pk_fma_f32 v[150:151], v[68:69], v[154:155], v[132:133] op_sel_hi:[1,0,1]
	v_and_b32_e32 v181, 0x7fffffff, v157
	v_and_b32_e32 v153, 0x7fffffff, v151
	v_and_b32_e32 v152, 0x7fffffff, v150
	v_pk_fma_f32 v[152:153], v[152:153], s[96:97], 1.0 op_sel_hi:[1,0,0]
	v_pk_mul_f32 v[174:175], v[150:151], v[150:151]
	v_rcp_f32_e32 v152, v152
	v_rcp_f32_e32 v153, v153
	v_pk_mul_f32 v[174:175], v[174:175], s[74:75] op_sel_hi:[1,0]
	v_and_b32_e32 v180, 0x7fffffff, v156
	v_exp_f32_e32 v174, v174
	v_pk_fma_f32 v[172:173], v[152:153], s[98:99], v[144:145] op_sel_hi:[1,0,0]
	v_exp_f32_e32 v175, v175
	v_pk_fma_f32 v[172:173], v[152:153], v[172:173], s[90:91] op_sel_hi:[1,1,0]
	v_pk_fma_f32 v[180:181], v[180:181], s[96:97], 1.0 op_sel_hi:[1,0,0]
	v_pk_fma_f32 v[172:173], v[152:153], v[172:173], s[4:5] op_sel_hi:[1,1,0]
	v_rcp_f32_e32 v180, v180
	v_pk_fma_f32 v[172:173], v[152:153], v[172:173], s[78:79] op_sel_hi:[1,1,0]
	v_rcp_f32_e32 v181, v181
	v_pk_mul_f32 v[152:153], v[152:153], v[172:173]
	v_cmp_gt_f32_e32 vcc, 0, v150
	v_pk_mul_f32 v[152:153], v[174:175], v[152:153]
	v_pk_mul_f32 v[172:173], v[156:157], v[156:157]
	v_pk_mul_f32 v[174:175], v[150:151], v[152:153]
	v_pk_fma_f32 v[152:153], v[150:151], v[152:153], v[150:151] neg_lo:[1,0,0] neg_hi:[1,0,0]
	v_pk_fma_f32 v[154:155], v[64:65], v[154:155], v[128:129] op_sel_hi:[1,0,1]
	v_cndmask_b32_e32 v174, v152, v174, vcc
	v_cmp_gt_f32_e32 vcc, 0, v151
	v_pk_fma_f32 v[150:151], v[180:181], s[98:99], v[144:145] op_sel_hi:[1,0,0]
	s_nop 0
	v_cndmask_b32_e32 v175, v153, v175, vcc
	v_pk_mul_f32 v[152:153], v[172:173], s[74:75] op_sel_hi:[1,0]
	v_pk_fma_f32 v[150:151], v[180:181], v[150:151], s[90:91] op_sel_hi:[1,1,0]
	v_exp_f32_e32 v152, v152
	v_exp_f32_e32 v153, v153
	v_pk_fma_f32 v[150:151], v[180:181], v[150:151], s[4:5] op_sel_hi:[1,1,0]
	v_and_b32_e32 v173, 0x7fffffff, v155
	v_and_b32_e32 v172, 0x7fffffff, v154
	v_pk_fma_f32 v[150:151], v[180:181], v[150:151], s[78:79] op_sel_hi:[1,1,0]
	v_pk_fma_f32 v[172:173], v[172:173], s[96:97], 1.0 op_sel_hi:[1,0,0]
	v_pk_mul_f32 v[150:151], v[180:181], v[150:151]
	v_rcp_f32_e32 v172, v172
	v_rcp_f32_e32 v173, v173
	v_pk_mul_f32 v[150:151], v[152:153], v[150:151]
	v_cmp_gt_f32_e32 vcc, 0, v156
	v_pk_mul_f32 v[152:153], v[156:157], v[150:151]
	v_pk_fma_f32 v[150:151], v[156:157], v[150:151], v[156:157] neg_lo:[1,0,0] neg_hi:[1,0,0]
	s_nop 0
	v_cndmask_b32_e32 v180, v150, v152, vcc
	v_cmp_gt_f32_e32 vcc, 0, v157
	v_pk_mul_f32 v[156:157], v[158:159], v[158:159]
	s_nop 0
	v_cndmask_b32_e32 v181, v151, v153, vcc
	v_pk_fma_f32 v[150:151], v[172:173], s[98:99], v[144:145] op_sel_hi:[1,0,0]
	v_pk_mul_f32 v[152:153], v[154:155], v[154:155]
	v_pk_fma_f32 v[150:151], v[172:173], v[150:151], s[90:91] op_sel_hi:[1,1,0]
	v_pk_mul_f32 v[152:153], v[152:153], s[74:75] op_sel_hi:[1,0]
	v_pk_fma_f32 v[150:151], v[172:173], v[150:151], s[4:5] op_sel_hi:[1,1,0]
	v_exp_f32_e32 v152, v152
	v_exp_f32_e32 v153, v153
	v_pk_fma_f32 v[150:151], v[172:173], v[150:151], s[78:79] op_sel_hi:[1,1,0]
	v_cmp_gt_f32_e32 vcc, 0, v154
	v_pk_mul_f32 v[150:151], v[172:173], v[150:151]
	v_and_b32_e32 v173, 0x7fffffff, v159
	v_and_b32_e32 v172, 0x7fffffff, v158
	v_pk_fma_f32 v[172:173], v[172:173], s[96:97], 1.0 op_sel_hi:[1,0,0]
	v_pk_mul_f32 v[150:151], v[152:153], v[150:151]
	v_rcp_f32_e32 v172, v172
	v_rcp_f32_e32 v173, v173
	v_pk_mul_f32 v[152:153], v[154:155], v[150:151]
	v_pk_fma_f32 v[150:151], v[154:155], v[150:151], v[154:155] neg_lo:[1,0,0] neg_hi:[1,0,0]
	s_nop 0
	v_cndmask_b32_e32 v154, v150, v152, vcc
	v_cmp_gt_f32_e32 vcc, 0, v155
	s_nop 1
	v_cndmask_b32_e32 v155, v151, v153, vcc
	v_pk_fma_f32 v[150:151], v[172:173], s[98:99], v[144:145] op_sel_hi:[1,0,0]
	v_pk_mul_f32 v[152:153], v[156:157], s[74:75] op_sel_hi:[1,0]
	v_pk_fma_f32 v[150:151], v[172:173], v[150:151], s[90:91] op_sel_hi:[1,1,0]
	v_exp_f32_e32 v152, v152
	v_exp_f32_e32 v153, v153
	v_pk_fma_f32 v[150:151], v[172:173], v[150:151], s[4:5] op_sel_hi:[1,1,0]
	v_cmp_gt_f32_e32 vcc, 0, v158
	v_pk_fma_f32 v[150:151], v[172:173], v[150:151], s[78:79] op_sel_hi:[1,1,0]
	s_nop 0
	v_pk_mul_f32 v[150:151], v[172:173], v[150:151]
	s_nop 0
	v_pk_mul_f32 v[150:151], v[152:153], v[150:151]
	s_nop 0
	v_pk_mul_f32 v[152:153], v[158:159], v[150:151]
	v_pk_fma_f32 v[150:151], v[158:159], v[150:151], v[158:159] neg_lo:[1,0,0] neg_hi:[1,0,0]
	s_nop 0
	v_cndmask_b32_e32 v156, v150, v152, vcc
	v_cmp_gt_f32_e32 vcc, 0, v159
	v_cvt_pk_bf16_f32 v150, v174, v175
	s_nop 1
	v_cndmask_b32_e32 v153, v151, v153, vcc
	v_cvt_pk_bf16_f32 v151, v180, v181
	v_cvt_pk_bf16_f32 v152, v154, v155
	v_cvt_pk_bf16_f32 v153, v156, v153
	global_store_dwordx4 v[148:149], v[150:153], off offset:256
	s_nop 0
	s_waitcnt vmcnt(13)
; __device__ __forceinline__ unsigned cvt_pk_bf16(float lo, float hi) { unsigned r; asm volatile("v_cvt_pk_bf16_f32 %0, %1, %2" : "=v"(r) : "v"(lo), "v"(hi)); return r; }
; __device__ __forceinline__ f32x2 gelu_pk(f32x2 v) {
;     const f32x2 av = __builtin_elementwise_abs(v), d = av * 0.2316418882f + 1.0f;
;     f32x2 t; t.x = __builtin_amdgcn_rcpf(d.x); t.y = __builtin_amdgcn_rcpf(d.y);
;     f32x2 q = t * 0.5307027145f + (-0.7265760135f); q = q * t + 0.7107068705f; q = q * t + (-0.142248368f); q = q * t + 0.127414796f; q = q * t;
;     const f32x2 s = (v * v) * (-0.72134752044f);
;     f32x2 e; e.x = __builtin_amdgcn_exp2f(s.x); e.y = __builtin_amdgcn_exp2f(s.y);
;     const f32x2 m = v * (q * e), r = v - m;
;     f32x2 o; o.x = v.x < 0.f ? m.x : r.x; o.y = v.y < 0.f ? m.y : r.y; return o;
; }
;     static __device__ __forceinline__ void run(const f32x4 (&acc)[2][2][4][2], const Unit& u, int wr, int wc, int fr, int fq, bf16_t* O, int ldc, const float* ssqA, const float* bvec) {
;     ...
;             for (int m = 0; m < 4; ++m) { const int row = row0 + ai * HALF + m * 16; const float r = row_scale(ssqA, nullptr, row); bf16_t* rowp = O + ((unsigned)row * (unsigned)ldc + (unsigned)col0);
; #pragma unroll
;                 for (int bj = 0; bj < 2; ++bj) { const f32x4 v0 = acc[ai][bj][m][0] * r + bv[bj][0], v1 = acc[ai][bj][m][1] * r + bv[bj][1];
;                     const f32x2 a = gelu_pk((f32x2){v0[0], v0[1]}), b2 = gelu_pk((f32x2){v0[2], v0[3]}), c = gelu_pk((f32x2){v1[0], v1[1]}), d = gelu_pk((f32x2){v1[2], v1[3]});
;                     u32x4 w; w.x = cvt_pk_bf16(a.x, a.y); w.y = cvt_pk_bf16(b2.x, b2.y); w.z = cvt_pk_bf16(c.x, c.y); w.w = cvt_pk_bf16(d.x, d.y);
;                     *(u32x4*)(rowp + bj * HALF) = w; }
	v_fmamk_f32 v148, v201, 0x3a800000, v222
	v_rsq_f32_e32 v154, v148
	v_lshl_add_u64 v[148:149], v[176:177], 1, s[2:3]
	v_add_u32_e32 v176, s8, v176
	v_pk_fma_f32 v[150:151], v[60:61], v[154:155], v[140:141] op_sel_hi:[1,0,1]
	s_nop 0
	v_and_b32_e32 v153, 0x7fffffff, v151
	v_and_b32_e32 v152, 0x7fffffff, v150
	v_pk_fma_f32 v[152:153], v[152:153], s[96:97], 1.0 op_sel_hi:[1,0,0]
	v_pk_mul_f32 v[180:181], v[150:151], v[150:151]
	v_rcp_f32_e32 v152, v152
	v_rcp_f32_e32 v153, v153
	v_pk_mul_f32 v[180:181], v[180:181], s[74:75] op_sel_hi:[1,0]
	v_pk_fma_f32 v[156:157], v[62:63], v[154:155], v[142:143] op_sel_hi:[1,0,1]
	v_exp_f32_e32 v180, v180
	v_pk_fma_f32 v[174:175], v[152:153], s[98:99], v[144:145] op_sel_hi:[1,0,0]
	v_exp_f32_e32 v181, v181
	v_pk_fma_f32 v[174:175], v[152:153], v[174:175], s[90:91] op_sel_hi:[1,1,0]
	v_and_b32_e32 v183, 0x7fffffff, v157
	v_pk_fma_f32 v[174:175], v[152:153], v[174:175], s[4:5] op_sel_hi:[1,1,0]
	v_and_b32_e32 v182, 0x7fffffff, v156
	v_pk_fma_f32 v[174:175], v[152:153], v[174:175], s[78:79] op_sel_hi:[1,1,0]
	v_pk_fma_f32 v[182:183], v[182:183], s[96:97], 1.0 op_sel_hi:[1,0,0]
	v_pk_mul_f32 v[152:153], v[152:153], v[174:175]
	v_rcp_f32_e32 v182, v182
	v_rcp_f32_e32 v183, v183
	v_pk_mul_f32 v[152:153], v[180:181], v[152:153]
	v_cmp_gt_f32_e32 vcc, 0, v150
	v_pk_mul_f32 v[180:181], v[150:151], v[152:153]
	v_pk_fma_f32 v[152:153], v[150:151], v[152:153], v[150:151] neg_lo:[1,0,0] neg_hi:[1,0,0]
	v_pk_fma_f32 v[158:159], v[58:59], v[154:155], v[138:139] op_sel_hi:[1,0,1]
	v_pk_fma_f32 v[172:173], v[56:57], v[154:155], v[136:137] op_sel_hi:[1,0,1]
	v_pk_mul_f32 v[174:175], v[156:157], v[156:157]
	v_cndmask_b32_e32 v155, v152, v180, vcc
	v_cmp_gt_f32_e32 vcc, 0, v151
	v_pk_fma_f32 v[150:151], v[182:183], s[98:99], v[144:145] op_sel_hi:[1,0,0]
	s_nop 0
	v_cndmask_b32_e32 v180, v153, v181, vcc
	v_pk_mul_f32 v[152:153], v[174:175], s[74:75] op_sel_hi:[1,0]
	v_pk_fma_f32 v[150:151], v[182:183], v[150:151], s[90:91] op_sel_hi:[1,1,0]
	v_exp_f32_e32 v152, v152
	v_exp_f32_e32 v153, v153
	v_pk_fma_f32 v[150:151], v[182:183], v[150:151], s[4:5] op_sel_hi:[1,1,0]
	v_and_b32_e32 v175, 0x7fffffff, v173
	v_and_b32_e32 v174, 0x7fffffff, v172
	v_pk_fma_f32 v[150:151], v[182:183], v[150:151], s[78:79] op_sel_hi:[1,1,0]
	v_pk_fma_f32 v[174:175], v[174:175], s[96:97], 1.0 op_sel_hi:[1,0,0]
	v_pk_mul_f32 v[150:151], v[182:183], v[150:151]
	v_rcp_f32_e32 v174, v174
	v_rcp_f32_e32 v175, v175
	v_pk_mul_f32 v[150:151], v[152:153], v[150:151]
	v_cmp_gt_f32_e32 vcc, 0, v156
	v_pk_mul_f32 v[152:153], v[156:157], v[150:151]
	v_pk_fma_f32 v[150:151], v[156:157], v[150:151], v[156:157] neg_lo:[1,0,0] neg_hi:[1,0,0]
	s_nop 0
	v_cndmask_b32_e32 v181, v150, v152, vcc
	v_cmp_gt_f32_e32 vcc, 0, v157
	v_pk_mul_f32 v[156:157], v[158:159], v[158:159]
	s_nop 0
	v_cndmask_b32_e32 v182, v151, v153, vcc
	v_pk_fma_f32 v[150:151], v[174:175], s[98:99], v[144:145] op_sel_hi:[1,0,0]
	v_pk_mul_f32 v[152:153], v[172:173], v[172:173]
	v_pk_fma_f32 v[150:151], v[174:175], v[150:151], s[90:91] op_sel_hi:[1,1,0]
	v_pk_mul_f32 v[152:153], v[152:153], s[74:75] op_sel_hi:[1,0]
	v_pk_fma_f32 v[150:151], v[174:175], v[150:151], s[4:5] op_sel_hi:[1,1,0]
	v_exp_f32_e32 v152, v152
	v_exp_f32_e32 v153, v153
	v_pk_fma_f32 v[150:151], v[174:175], v[150:151], s[78:79] op_sel_hi:[1,1,0]
	v_cmp_gt_f32_e32 vcc, 0, v172
	v_pk_mul_f32 v[150:151], v[174:175], v[150:151]
	v_and_b32_e32 v175, 0x7fffffff, v159
	v_and_b32_e32 v174, 0x7fffffff, v158
	v_pk_fma_f32 v[174:175], v[174:175], s[96:97], 1.0 op_sel_hi:[1,0,0]
	v_pk_mul_f32 v[150:151], v[152:153], v[150:151]
	v_rcp_f32_e32 v174, v174
	v_rcp_f32_e32 v175, v175
	v_pk_mul_f32 v[152:153], v[172:173], v[150:151]
	v_pk_fma_f32 v[150:151], v[172:173], v[150:151], v[172:173] neg_lo:[1,0,0] neg_hi:[1,0,0]
	s_nop 0
	v_cndmask_b32_e32 v172, v150, v152, vcc
	v_cmp_gt_f32_e32 vcc, 0, v173
	s_nop 1
	v_cndmask_b32_e32 v173, v151, v153, vcc
	v_pk_fma_f32 v[150:151], v[174:175], s[98:99], v[144:145] op_sel_hi:[1,0,0]
	v_pk_mul_f32 v[152:153], v[156:157], s[74:75] op_sel_hi:[1,0]
	v_pk_fma_f32 v[150:151], v[174:175], v[150:151], s[90:91] op_sel_hi:[1,1,0]
	v_exp_f32_e32 v152, v152
	v_exp_f32_e32 v153, v153
	v_pk_fma_f32 v[150:151], v[174:175], v[150:151], s[4:5] op_sel_hi:[1,1,0]
	v_cmp_gt_f32_e32 vcc, 0, v158
	v_pk_fma_f32 v[150:151], v[174:175], v[150:151], s[78:79] op_sel_hi:[1,1,0]
	s_nop 0
	v_pk_mul_f32 v[150:151], v[174:175], v[150:151]
	s_nop 0
	v_pk_mul_f32 v[150:151], v[152:153], v[150:151]
	s_nop 0
	v_pk_mul_f32 v[152:153], v[158:159], v[150:151]
	v_pk_fma_f32 v[150:151], v[158:159], v[150:151], v[158:159] neg_lo:[1,0,0] neg_hi:[1,0,0]
	s_nop 0
	v_cndmask_b32_e32 v156, v150, v152, vcc
	v_cmp_gt_f32_e32 vcc, 0, v159
	v_cvt_pk_bf16_f32 v150, v155, v180
	v_pk_fma_f32 v[158:159], v[50:51], v[154:155], v[130:131] op_sel_hi:[1,0,1]
	s_nop 0
	v_cndmask_b32_e32 v153, v151, v153, vcc
	v_cvt_pk_bf16_f32 v151, v181, v182
	v_cvt_pk_bf16_f32 v152, v172, v173
	v_cvt_pk_bf16_f32 v153, v156, v153
	global_store_dwordx4 v[148:149], v[150:153], off
	v_pk_fma_f32 v[156:157], v[54:55], v[154:155], v[134:135] op_sel_hi:[1,0,1]
	s_nop 0
	v_pk_fma_f32 v[150:151], v[52:53], v[154:155], v[132:133] op_sel_hi:[1,0,1]
	v_and_b32_e32 v181, 0x7fffffff, v157
	v_and_b32_e32 v153, 0x7fffffff, v151
	v_and_b32_e32 v152, 0x7fffffff, v150
	v_pk_fma_f32 v[152:153], v[152:153], s[96:97], 1.0 op_sel_hi:[1,0,0]
	v_pk_mul_f32 v[174:175], v[150:151], v[150:151]
	v_rcp_f32_e32 v152, v152
	v_rcp_f32_e32 v153, v153
	v_pk_mul_f32 v[174:175], v[174:175], s[74:75] op_sel_hi:[1,0]
	v_and_b32_e32 v180, 0x7fffffff, v156
	v_exp_f32_e32 v174, v174
	v_pk_fma_f32 v[172:173], v[152:153], s[98:99], v[144:145] op_sel_hi:[1,0,0]
; __device__ __forceinline__ unsigned cvt_pk_bf16(float lo, float hi) { unsigned r; asm volatile("v_cvt_pk_bf16_f32 %0, %1, %2" : "=v"(r) : "v"(lo), "v"(hi)); return r; }
; __device__ __forceinline__ f32x2 gelu_pk(f32x2 v) {
;     const f32x2 av = __builtin_elementwise_abs(v), d = av * 0.2316418882f + 1.0f;
;     f32x2 t; t.x = __builtin_amdgcn_rcpf(d.x); t.y = __builtin_amdgcn_rcpf(d.y);
;     f32x2 q = t * 0.5307027145f + (-0.7265760135f); q = q * t + 0.7107068705f; q = q * t + (-0.142248368f); q = q * t + 0.127414796f; q = q * t;
;     const f32x2 s = (v * v) * (-0.72134752044f);
;     f32x2 e; e.x = __builtin_amdgcn_exp2f(s.x); e.y = __builtin_amdgcn_exp2f(s.y);
;     const f32x2 m = v * (q * e), r = v - m;
;     f32x2 o; o.x = v.x < 0.f ? m.x : r.x; o.y = v.y < 0.f ? m.y : r.y; return o;
; }
;     static __device__ __forceinline__ void run(const f32x4 (&acc)[2][2][4][2], const Unit& u, int wr, int wc, int fr, int fq, bf16_t* O, int ldc, const float* ssqA, const float* bvec) {
;     ...
;             for (int m = 0; m < 4; ++m) { const int row = row0 + ai * HALF + m * 16; const float r = row_scale(ssqA, nullptr, row); bf16_t* rowp = O + ((unsigned)row * (unsigned)ldc + (unsigned)col0);
; #pragma unroll
;                 for (int bj = 0; bj < 2; ++bj) { const f32x4 v0 = acc[ai][bj][m][0] * r + bv[bj][0], v1 = acc[ai][bj][m][1] * r + bv[bj][1];
;                     const f32x2 a = gelu_pk((f32x2){v0[0], v0[1]}), b2 = gelu_pk((f32x2){v0[2], v0[3]}), c = gelu_pk((f32x2){v1[0], v1[1]}), d = gelu_pk((f32x2){v1[2], v1[3]});
;                     u32x4 w; w.x = cvt_pk_bf16(a.x, a.y); w.y = cvt_pk_bf16(b2.x, b2.y); w.z = cvt_pk_bf16(c.x, c.y); w.w = cvt_pk_bf16(d.x, d.y);
;                     *(u32x4*)(rowp + bj * HALF) = w; }
	v_exp_f32_e32 v175, v175
	v_pk_fma_f32 v[172:173], v[152:153], v[172:173], s[90:91] op_sel_hi:[1,1,0]
	v_pk_fma_f32 v[180:181], v[180:181], s[96:97], 1.0 op_sel_hi:[1,0,0]
	v_pk_fma_f32 v[172:173], v[152:153], v[172:173], s[4:5] op_sel_hi:[1,1,0]
	v_rcp_f32_e32 v180, v180
	v_pk_fma_f32 v[172:173], v[152:153], v[172:173], s[78:79] op_sel_hi:[1,1,0]
	v_rcp_f32_e32 v181, v181
	v_pk_mul_f32 v[152:153], v[152:153], v[172:173]
	v_cmp_gt_f32_e32 vcc, 0, v150
	v_pk_mul_f32 v[152:153], v[174:175], v[152:153]
	v_pk_mul_f32 v[172:173], v[156:157], v[156:157]
	v_pk_mul_f32 v[174:175], v[150:151], v[152:153]
	v_pk_fma_f32 v[152:153], v[150:151], v[152:153], v[150:151] neg_lo:[1,0,0] neg_hi:[1,0,0]
	v_pk_fma_f32 v[154:155], v[48:49], v[154:155], v[128:129] op_sel_hi:[1,0,1]
	v_cndmask_b32_e32 v174, v152, v174, vcc
	v_cmp_gt_f32_e32 vcc, 0, v151
	v_pk_fma_f32 v[150:151], v[180:181], s[98:99], v[144:145] op_sel_hi:[1,0,0]
	s_nop 0
	v_cndmask_b32_e32 v175, v153, v175, vcc
	v_pk_mul_f32 v[152:153], v[172:173], s[74:75] op_sel_hi:[1,0]
	v_pk_fma_f32 v[150:151], v[180:181], v[150:151], s[90:91] op_sel_hi:[1,1,0]
	v_exp_f32_e32 v152, v152
	v_exp_f32_e32 v153, v153
	v_pk_fma_f32 v[150:151], v[180:181], v[150:151], s[4:5] op_sel_hi:[1,1,0]
	v_and_b32_e32 v173, 0x7fffffff, v155
	v_and_b32_e32 v172, 0x7fffffff, v154
	v_pk_fma_f32 v[150:151], v[180:181], v[150:151], s[78:79] op_sel_hi:[1,1,0]
	v_pk_fma_f32 v[172:173], v[172:173], s[96:97], 1.0 op_sel_hi:[1,0,0]
	v_pk_mul_f32 v[150:151], v[180:181], v[150:151]
	v_rcp_f32_e32 v172, v172
	v_rcp_f32_e32 v173, v173
	v_pk_mul_f32 v[150:151], v[152:153], v[150:151]
	v_cmp_gt_f32_e32 vcc, 0, v156
	v_pk_mul_f32 v[152:153], v[156:157], v[150:151]
	v_pk_fma_f32 v[150:151], v[156:157], v[150:151], v[156:157] neg_lo:[1,0,0] neg_hi:[1,0,0]
	s_nop 0
	v_cndmask_b32_e32 v180, v150, v152, vcc
	v_cmp_gt_f32_e32 vcc, 0, v157
	v_pk_mul_f32 v[156:157], v[158:159], v[158:159]
	s_nop 0
	v_cndmask_b32_e32 v181, v151, v153, vcc
	v_pk_fma_f32 v[150:151], v[172:173], s[98:99], v[144:145] op_sel_hi:[1,0,0]
	v_pk_mul_f32 v[152:153], v[154:155], v[154:155]
	v_pk_fma_f32 v[150:151], v[172:173], v[150:151], s[90:91] op_sel_hi:[1,1,0]
	v_pk_mul_f32 v[152:153], v[152:153], s[74:75] op_sel_hi:[1,0]
	v_pk_fma_f32 v[150:151], v[172:173], v[150:151], s[4:5] op_sel_hi:[1,1,0]
	v_exp_f32_e32 v152, v152
	v_exp_f32_e32 v153, v153
	v_pk_fma_f32 v[150:151], v[172:173], v[150:151], s[78:79] op_sel_hi:[1,1,0]
	v_cmp_gt_f32_e32 vcc, 0, v154
	v_pk_mul_f32 v[150:151], v[172:173], v[150:151]
	v_and_b32_e32 v173, 0x7fffffff, v159
	v_and_b32_e32 v172, 0x7fffffff, v158
	v_pk_fma_f32 v[172:173], v[172:173], s[96:97], 1.0 op_sel_hi:[1,0,0]
	v_pk_mul_f32 v[150:151], v[152:153], v[150:151]
	v_rcp_f32_e32 v172, v172
	v_rcp_f32_e32 v173, v173
	v_pk_mul_f32 v[152:153], v[154:155], v[150:151]
	v_pk_fma_f32 v[150:151], v[154:155], v[150:151], v[154:155] neg_lo:[1,0,0] neg_hi:[1,0,0]
	s_nop 0
	v_cndmask_b32_e32 v154, v150, v152, vcc
	v_cmp_gt_f32_e32 vcc, 0, v155
	s_nop 1
	v_cndmask_b32_e32 v155, v151, v153, vcc
	v_pk_fma_f32 v[150:151], v[172:173], s[98:99], v[144:145] op_sel_hi:[1,0,0]
	v_pk_mul_f32 v[152:153], v[156:157], s[74:75] op_sel_hi:[1,0]
	v_pk_fma_f32 v[150:151], v[172:173], v[150:151], s[90:91] op_sel_hi:[1,1,0]
	v_exp_f32_e32 v152, v152
	v_exp_f32_e32 v153, v153
	v_pk_fma_f32 v[150:151], v[172:173], v[150:151], s[4:5] op_sel_hi:[1,1,0]
	v_cmp_gt_f32_e32 vcc, 0, v158
	v_pk_fma_f32 v[150:151], v[172:173], v[150:151], s[78:79] op_sel_hi:[1,1,0]
	s_nop 0
	v_pk_mul_f32 v[150:151], v[172:173], v[150:151]
	s_nop 0
	v_pk_mul_f32 v[150:151], v[152:153], v[150:151]
	s_nop 0
	v_pk_mul_f32 v[152:153], v[158:159], v[150:151]
	v_pk_fma_f32 v[150:151], v[158:159], v[150:151], v[158:159] neg_lo:[1,0,0] neg_hi:[1,0,0]
	s_nop 0
	v_cndmask_b32_e32 v156, v150, v152, vcc
	v_cmp_gt_f32_e32 vcc, 0, v159
	v_cvt_pk_bf16_f32 v150, v174, v175
	s_nop 1
	v_cndmask_b32_e32 v153, v151, v153, vcc
	v_cvt_pk_bf16_f32 v151, v180, v181
	v_cvt_pk_bf16_f32 v152, v154, v155
	v_cvt_pk_bf16_f32 v153, v156, v153
	global_store_dwordx4 v[148:149], v[150:153], off offset:256
	s_nop 0
	s_waitcnt vmcnt(14)
	v_fmamk_f32 v148, v202, 0x3a800000, v222
	v_rsq_f32_e32 v154, v148
	v_lshl_add_u64 v[148:149], v[176:177], 1, s[2:3]
	v_add_u32_e32 v176, s8, v176
	v_pk_fma_f32 v[150:151], v[44:45], v[154:155], v[140:141] op_sel_hi:[1,0,1]
	s_nop 0
	v_and_b32_e32 v153, 0x7fffffff, v151
	v_and_b32_e32 v152, 0x7fffffff, v150
	v_pk_fma_f32 v[152:153], v[152:153], s[96:97], 1.0 op_sel_hi:[1,0,0]
	v_pk_mul_f32 v[180:181], v[150:151], v[150:151]
	v_rcp_f32_e32 v152, v152
	v_rcp_f32_e32 v153, v153
	v_pk_mul_f32 v[180:181], v[180:181], s[74:75] op_sel_hi:[1,0]
	v_pk_fma_f32 v[156:157], v[46:47], v[154:155], v[142:143] op_sel_hi:[1,0,1]
	v_exp_f32_e32 v180, v180
	v_pk_fma_f32 v[174:175], v[152:153], s[98:99], v[144:145] op_sel_hi:[1,0,0]
	v_exp_f32_e32 v181, v181
	v_pk_fma_f32 v[174:175], v[152:153], v[174:175], s[90:91] op_sel_hi:[1,1,0]
	v_and_b32_e32 v183, 0x7fffffff, v157
	v_pk_fma_f32 v[174:175], v[152:153], v[174:175], s[4:5] op_sel_hi:[1,1,0]
	v_and_b32_e32 v182, 0x7fffffff, v156
	v_pk_fma_f32 v[174:175], v[152:153], v[174:175], s[78:79] op_sel_hi:[1,1,0]
	v_pk_fma_f32 v[182:183], v[182:183], s[96:97], 1.0 op_sel_hi:[1,0,0]
	v_pk_mul_f32 v[152:153], v[152:153], v[174:175]
	v_rcp_f32_e32 v182, v182
	v_rcp_f32_e32 v183, v183
	v_pk_mul_f32 v[152:153], v[180:181], v[152:153]
	v_cmp_gt_f32_e32 vcc, 0, v150
	v_pk_mul_f32 v[180:181], v[150:151], v[152:153]
	v_pk_fma_f32 v[152:153], v[150:151], v[152:153], v[150:151] neg_lo:[1,0,0] neg_hi:[1,0,0]
	v_pk_fma_f32 v[158:159], v[42:43], v[154:155], v[138:139] op_sel_hi:[1,0,1]
; __device__ __forceinline__ unsigned cvt_pk_bf16(float lo, float hi) { unsigned r; asm volatile("v_cvt_pk_bf16_f32 %0, %1, %2" : "=v"(r) : "v"(lo), "v"(hi)); return r; }
; __device__ __forceinline__ f32x2 gelu_pk(f32x2 v) {
;     const f32x2 av = __builtin_elementwise_abs(v), d = av * 0.2316418882f + 1.0f;
;     f32x2 t; t.x = __builtin_amdgcn_rcpf(d.x); t.y = __builtin_amdgcn_rcpf(d.y);
;     f32x2 q = t * 0.5307027145f + (-0.7265760135f); q = q * t + 0.7107068705f; q = q * t + (-0.142248368f); q = q * t + 0.127414796f; q = q * t;
;     const f32x2 s = (v * v) * (-0.72134752044f);
;     f32x2 e; e.x = __builtin_amdgcn_exp2f(s.x); e.y = __builtin_amdgcn_exp2f(s.y);
;     const f32x2 m = v * (q * e), r = v - m;
;     f32x2 o; o.x = v.x < 0.f ? m.x : r.x; o.y = v.y < 0.f ? m.y : r.y; return o;
; }
;     static __device__ __forceinline__ void run(const f32x4 (&acc)[2][2][4][2], const Unit& u, int wr, int wc, int fr, int fq, bf16_t* O, int ldc, const float* ssqA, const float* bvec) {
;     ...
;             for (int m = 0; m < 4; ++m) { const int row = row0 + ai * HALF + m * 16; const float r = row_scale(ssqA, nullptr, row); bf16_t* rowp = O + ((unsigned)row * (unsigned)ldc + (unsigned)col0);
; #pragma unroll
;                 for (int bj = 0; bj < 2; ++bj) { const f32x4 v0 = acc[ai][bj][m][0] * r + bv[bj][0], v1 = acc[ai][bj][m][1] * r + bv[bj][1];
;                     const f32x2 a = gelu_pk((f32x2){v0[0], v0[1]}), b2 = gelu_pk((f32x2){v0[2], v0[3]}), c = gelu_pk((f32x2){v1[0], v1[1]}), d = gelu_pk((f32x2){v1[2], v1[3]});
;                     u32x4 w; w.x = cvt_pk_bf16(a.x, a.y); w.y = cvt_pk_bf16(b2.x, b2.y); w.z = cvt_pk_bf16(c.x, c.y); w.w = cvt_pk_bf16(d.x, d.y);
;                     *(u32x4*)(rowp + bj * HALF) = w; }
	v_pk_fma_f32 v[172:173], v[40:41], v[154:155], v[136:137] op_sel_hi:[1,0,1]
	v_pk_mul_f32 v[174:175], v[156:157], v[156:157]
	v_cndmask_b32_e32 v155, v152, v180, vcc
	v_cmp_gt_f32_e32 vcc, 0, v151
	v_pk_fma_f32 v[150:151], v[182:183], s[98:99], v[144:145] op_sel_hi:[1,0,0]
	s_nop 0
	v_cndmask_b32_e32 v180, v153, v181, vcc
	v_pk_mul_f32 v[152:153], v[174:175], s[74:75] op_sel_hi:[1,0]
	v_pk_fma_f32 v[150:151], v[182:183], v[150:151], s[90:91] op_sel_hi:[1,1,0]
	v_exp_f32_e32 v152, v152
	v_exp_f32_e32 v153, v153
	v_pk_fma_f32 v[150:151], v[182:183], v[150:151], s[4:5] op_sel_hi:[1,1,0]
	v_and_b32_e32 v175, 0x7fffffff, v173
	v_and_b32_e32 v174, 0x7fffffff, v172
	v_pk_fma_f32 v[150:151], v[182:183], v[150:151], s[78:79] op_sel_hi:[1,1,0]
	v_pk_fma_f32 v[174:175], v[174:175], s[96:97], 1.0 op_sel_hi:[1,0,0]
	v_pk_mul_f32 v[150:151], v[182:183], v[150:151]
	v_rcp_f32_e32 v174, v174
	v_rcp_f32_e32 v175, v175
	v_pk_mul_f32 v[150:151], v[152:153], v[150:151]
	v_cmp_gt_f32_e32 vcc, 0, v156
	v_pk_mul_f32 v[152:153], v[156:157], v[150:151]
	v_pk_fma_f32 v[150:151], v[156:157], v[150:151], v[156:157] neg_lo:[1,0,0] neg_hi:[1,0,0]
	s_nop 0
	v_cndmask_b32_e32 v181, v150, v152, vcc
	v_cmp_gt_f32_e32 vcc, 0, v157
	v_pk_mul_f32 v[156:157], v[158:159], v[158:159]
	s_nop 0
	v_cndmask_b32_e32 v182, v151, v153, vcc
	v_pk_fma_f32 v[150:151], v[174:175], s[98:99], v[144:145] op_sel_hi:[1,0,0]
	v_pk_mul_f32 v[152:153], v[172:173], v[172:173]
	v_pk_fma_f32 v[150:151], v[174:175], v[150:151], s[90:91] op_sel_hi:[1,1,0]
	v_pk_mul_f32 v[152:153], v[152:153], s[74:75] op_sel_hi:[1,0]
	v_pk_fma_f32 v[150:151], v[174:175], v[150:151], s[4:5] op_sel_hi:[1,1,0]
	v_exp_f32_e32 v152, v152
	v_exp_f32_e32 v153, v153
	v_pk_fma_f32 v[150:151], v[174:175], v[150:151], s[78:79] op_sel_hi:[1,1,0]
	v_cmp_gt_f32_e32 vcc, 0, v172
	v_pk_mul_f32 v[150:151], v[174:175], v[150:151]
	v_and_b32_e32 v175, 0x7fffffff, v159
	v_and_b32_e32 v174, 0x7fffffff, v158
	v_pk_fma_f32 v[174:175], v[174:175], s[96:97], 1.0 op_sel_hi:[1,0,0]
	v_pk_mul_f32 v[150:151], v[152:153], v[150:151]
	v_rcp_f32_e32 v174, v174
	v_rcp_f32_e32 v175, v175
	v_pk_mul_f32 v[152:153], v[172:173], v[150:151]
	v_pk_fma_f32 v[150:151], v[172:173], v[150:151], v[172:173] neg_lo:[1,0,0] neg_hi:[1,0,0]
	s_nop 0
	v_cndmask_b32_e32 v172, v150, v152, vcc
	v_cmp_gt_f32_e32 vcc, 0, v173
	s_nop 1
	v_cndmask_b32_e32 v173, v151, v153, vcc
	v_pk_fma_f32 v[150:151], v[174:175], s[98:99], v[144:145] op_sel_hi:[1,0,0]
	v_pk_mul_f32 v[152:153], v[156:157], s[74:75] op_sel_hi:[1,0]
	v_pk_fma_f32 v[150:151], v[174:175], v[150:151], s[90:91] op_sel_hi:[1,1,0]
	v_exp_f32_e32 v152, v152
	v_exp_f32_e32 v153, v153
	v_pk_fma_f32 v[150:151], v[174:175], v[150:151], s[4:5] op_sel_hi:[1,1,0]
	v_cmp_gt_f32_e32 vcc, 0, v158
	v_pk_fma_f32 v[150:151], v[174:175], v[150:151], s[78:79] op_sel_hi:[1,1,0]
	s_nop 0
	v_pk_mul_f32 v[150:151], v[174:175], v[150:151]
	s_nop 0
	v_pk_mul_f32 v[150:151], v[152:153], v[150:151]
	s_nop 0
	v_pk_mul_f32 v[152:153], v[158:159], v[150:151]
	v_pk_fma_f32 v[150:151], v[158:159], v[150:151], v[158:159] neg_lo:[1,0,0] neg_hi:[1,0,0]
	s_nop 0
	v_cndmask_b32_e32 v156, v150, v152, vcc
	v_cmp_gt_f32_e32 vcc, 0, v159
	v_cvt_pk_bf16_f32 v150, v155, v180
	v_pk_fma_f32 v[158:159], v[34:35], v[154:155], v[130:131] op_sel_hi:[1,0,1]
	s_nop 0
	v_cndmask_b32_e32 v153, v151, v153, vcc
	v_cvt_pk_bf16_f32 v151, v181, v182
	v_cvt_pk_bf16_f32 v152, v172, v173
	v_cvt_pk_bf16_f32 v153, v156, v153
	global_store_dwordx4 v[148:149], v[150:153], off
	v_pk_fma_f32 v[156:157], v[38:39], v[154:155], v[134:135] op_sel_hi:[1,0,1]
	s_nop 0
	v_pk_fma_f32 v[150:151], v[36:37], v[154:155], v[132:133] op_sel_hi:[1,0,1]
	v_and_b32_e32 v181, 0x7fffffff, v157
	v_and_b32_e32 v153, 0x7fffffff, v151
	v_and_b32_e32 v152, 0x7fffffff, v150
	v_pk_fma_f32 v[152:153], v[152:153], s[96:97], 1.0 op_sel_hi:[1,0,0]
	v_pk_mul_f32 v[174:175], v[150:151], v[150:151]
	v_rcp_f32_e32 v152, v152
	v_rcp_f32_e32 v153, v153
	v_pk_mul_f32 v[174:175], v[174:175], s[74:75] op_sel_hi:[1,0]
	v_and_b32_e32 v180, 0x7fffffff, v156
	v_exp_f32_e32 v174, v174
	v_pk_fma_f32 v[172:173], v[152:153], s[98:99], v[144:145] op_sel_hi:[1,0,0]
	v_exp_f32_e32 v175, v175
	v_pk_fma_f32 v[172:173], v[152:153], v[172:173], s[90:91] op_sel_hi:[1,1,0]
	v_pk_fma_f32 v[180:181], v[180:181], s[96:97], 1.0 op_sel_hi:[1,0,0]
	v_pk_fma_f32 v[172:173], v[152:153], v[172:173], s[4:5] op_sel_hi:[1,1,0]
	v_rcp_f32_e32 v180, v180
	v_pk_fma_f32 v[172:173], v[152:153], v[172:173], s[78:79] op_sel_hi:[1,1,0]
	v_rcp_f32_e32 v181, v181
	v_pk_mul_f32 v[152:153], v[152:153], v[172:173]
	v_cmp_gt_f32_e32 vcc, 0, v150
	v_pk_mul_f32 v[152:153], v[174:175], v[152:153]
	v_pk_mul_f32 v[172:173], v[156:157], v[156:157]
	v_pk_mul_f32 v[174:175], v[150:151], v[152:153]
	v_pk_fma_f32 v[152:153], v[150:151], v[152:153], v[150:151] neg_lo:[1,0,0] neg_hi:[1,0,0]
	v_pk_fma_f32 v[154:155], v[32:33], v[154:155], v[128:129] op_sel_hi:[1,0,1]
	v_cndmask_b32_e32 v174, v152, v174, vcc
	v_cmp_gt_f32_e32 vcc, 0, v151
	v_pk_fma_f32 v[150:151], v[180:181], s[98:99], v[144:145] op_sel_hi:[1,0,0]
	s_nop 0
	v_cndmask_b32_e32 v175, v153, v175, vcc
	v_pk_mul_f32 v[152:153], v[172:173], s[74:75] op_sel_hi:[1,0]
	v_pk_fma_f32 v[150:151], v[180:181], v[150:151], s[90:91] op_sel_hi:[1,1,0]
	v_exp_f32_e32 v152, v152
	v_exp_f32_e32 v153, v153
	v_pk_fma_f32 v[150:151], v[180:181], v[150:151], s[4:5] op_sel_hi:[1,1,0]
	v_and_b32_e32 v173, 0x7fffffff, v155
	v_and_b32_e32 v172, 0x7fffffff, v154
	v_pk_fma_f32 v[150:151], v[180:181], v[150:151], s[78:79] op_sel_hi:[1,1,0]
	v_pk_fma_f32 v[172:173], v[172:173], s[96:97], 1.0 op_sel_hi:[1,0,0]
; __device__ __forceinline__ unsigned cvt_pk_bf16(float lo, float hi) { unsigned r; asm volatile("v_cvt_pk_bf16_f32 %0, %1, %2" : "=v"(r) : "v"(lo), "v"(hi)); return r; }
; __device__ __forceinline__ f32x2 gelu_pk(f32x2 v) {
;     const f32x2 av = __builtin_elementwise_abs(v), d = av * 0.2316418882f + 1.0f;
;     f32x2 t; t.x = __builtin_amdgcn_rcpf(d.x); t.y = __builtin_amdgcn_rcpf(d.y);
;     f32x2 q = t * 0.5307027145f + (-0.7265760135f); q = q * t + 0.7107068705f; q = q * t + (-0.142248368f); q = q * t + 0.127414796f; q = q * t;
;     const f32x2 s = (v * v) * (-0.72134752044f);
;     f32x2 e; e.x = __builtin_amdgcn_exp2f(s.x); e.y = __builtin_amdgcn_exp2f(s.y);
;     const f32x2 m = v * (q * e), r = v - m;
;     f32x2 o; o.x = v.x < 0.f ? m.x : r.x; o.y = v.y < 0.f ? m.y : r.y; return o;
; }
;     static __device__ __forceinline__ void run(const f32x4 (&acc)[2][2][4][2], const Unit& u, int wr, int wc, int fr, int fq, bf16_t* O, int ldc, const float* ssqA, const float* bvec) {
;     ...
;             for (int m = 0; m < 4; ++m) { const int row = row0 + ai * HALF + m * 16; const float r = row_scale(ssqA, nullptr, row); bf16_t* rowp = O + ((unsigned)row * (unsigned)ldc + (unsigned)col0);
; #pragma unroll
;                 for (int bj = 0; bj < 2; ++bj) { const f32x4 v0 = acc[ai][bj][m][0] * r + bv[bj][0], v1 = acc[ai][bj][m][1] * r + bv[bj][1];
;                     const f32x2 a = gelu_pk((f32x2){v0[0], v0[1]}), b2 = gelu_pk((f32x2){v0[2], v0[3]}), c = gelu_pk((f32x2){v1[0], v1[1]}), d = gelu_pk((f32x2){v1[2], v1[3]});
;                     u32x4 w; w.x = cvt_pk_bf16(a.x, a.y); w.y = cvt_pk_bf16(b2.x, b2.y); w.z = cvt_pk_bf16(c.x, c.y); w.w = cvt_pk_bf16(d.x, d.y);
;                     *(u32x4*)(rowp + bj * HALF) = w; }
	v_pk_mul_f32 v[150:151], v[180:181], v[150:151]
	v_rcp_f32_e32 v172, v172
	v_rcp_f32_e32 v173, v173
	v_pk_mul_f32 v[150:151], v[152:153], v[150:151]
	v_cmp_gt_f32_e32 vcc, 0, v156
	v_pk_mul_f32 v[152:153], v[156:157], v[150:151]
	v_pk_fma_f32 v[150:151], v[156:157], v[150:151], v[156:157] neg_lo:[1,0,0] neg_hi:[1,0,0]
	s_nop 0
	v_cndmask_b32_e32 v180, v150, v152, vcc
	v_cmp_gt_f32_e32 vcc, 0, v157
	v_pk_mul_f32 v[156:157], v[158:159], v[158:159]
	s_nop 0
	v_cndmask_b32_e32 v181, v151, v153, vcc
	v_pk_fma_f32 v[150:151], v[172:173], s[98:99], v[144:145] op_sel_hi:[1,0,0]
	v_pk_mul_f32 v[152:153], v[154:155], v[154:155]
	v_pk_fma_f32 v[150:151], v[172:173], v[150:151], s[90:91] op_sel_hi:[1,1,0]
	v_pk_mul_f32 v[152:153], v[152:153], s[74:75] op_sel_hi:[1,0]
	v_pk_fma_f32 v[150:151], v[172:173], v[150:151], s[4:5] op_sel_hi:[1,1,0]
	v_exp_f32_e32 v152, v152
	v_exp_f32_e32 v153, v153
	v_pk_fma_f32 v[150:151], v[172:173], v[150:151], s[78:79] op_sel_hi:[1,1,0]
	v_cmp_gt_f32_e32 vcc, 0, v154
	v_pk_mul_f32 v[150:151], v[172:173], v[150:151]
	v_and_b32_e32 v173, 0x7fffffff, v159
	v_and_b32_e32 v172, 0x7fffffff, v158
	v_pk_fma_f32 v[172:173], v[172:173], s[96:97], 1.0 op_sel_hi:[1,0,0]
	v_pk_mul_f32 v[150:151], v[152:153], v[150:151]
	v_rcp_f32_e32 v172, v172
	v_rcp_f32_e32 v173, v173
	v_pk_mul_f32 v[152:153], v[154:155], v[150:151]
	v_pk_fma_f32 v[150:151], v[154:155], v[150:151], v[154:155] neg_lo:[1,0,0] neg_hi:[1,0,0]
	s_nop 0
	v_cndmask_b32_e32 v154, v150, v152, vcc
	v_cmp_gt_f32_e32 vcc, 0, v155
	s_nop 1
	v_cndmask_b32_e32 v155, v151, v153, vcc
	v_pk_fma_f32 v[150:151], v[172:173], s[98:99], v[144:145] op_sel_hi:[1,0,0]
	v_pk_mul_f32 v[152:153], v[156:157], s[74:75] op_sel_hi:[1,0]
	v_pk_fma_f32 v[150:151], v[172:173], v[150:151], s[90:91] op_sel_hi:[1,1,0]
	v_exp_f32_e32 v152, v152
	v_exp_f32_e32 v153, v153
	v_pk_fma_f32 v[150:151], v[172:173], v[150:151], s[4:5] op_sel_hi:[1,1,0]
	v_cmp_gt_f32_e32 vcc, 0, v158
	v_pk_fma_f32 v[150:151], v[172:173], v[150:151], s[78:79] op_sel_hi:[1,1,0]
	s_nop 0
	v_pk_mul_f32 v[150:151], v[172:173], v[150:151]
	s_nop 0
	v_pk_mul_f32 v[150:151], v[152:153], v[150:151]
	s_nop 0
	v_pk_mul_f32 v[152:153], v[158:159], v[150:151]
	v_pk_fma_f32 v[150:151], v[158:159], v[150:151], v[158:159] neg_lo:[1,0,0] neg_hi:[1,0,0]
	s_nop 0
	v_cndmask_b32_e32 v156, v150, v152, vcc
	v_cmp_gt_f32_e32 vcc, 0, v159
	v_cvt_pk_bf16_f32 v150, v174, v175
	s_nop 1
	v_cndmask_b32_e32 v153, v151, v153, vcc
	v_cvt_pk_bf16_f32 v151, v180, v181
	v_cvt_pk_bf16_f32 v152, v154, v155
	v_cvt_pk_bf16_f32 v153, v156, v153
	global_store_dwordx4 v[148:149], v[150:153], off offset:256
	s_nop 0
	s_waitcnt vmcnt(15)
	v_fmamk_f32 v148, v203, 0x3a800000, v222
	v_rsq_f32_e32 v154, v148
	v_lshl_add_u64 v[148:149], v[176:177], 1, s[2:3]
	v_add_u32_e32 v176, s8, v176
	v_pk_fma_f32 v[150:151], v[28:29], v[154:155], v[140:141] op_sel_hi:[1,0,1]
	s_nop 0
	v_and_b32_e32 v153, 0x7fffffff, v151
	v_and_b32_e32 v152, 0x7fffffff, v150
	v_pk_fma_f32 v[152:153], v[152:153], s[96:97], 1.0 op_sel_hi:[1,0,0]
	v_pk_mul_f32 v[180:181], v[150:151], v[150:151]
	v_rcp_f32_e32 v152, v152
	v_rcp_f32_e32 v153, v153
	v_pk_mul_f32 v[180:181], v[180:181], s[74:75] op_sel_hi:[1,0]
	v_pk_fma_f32 v[156:157], v[30:31], v[154:155], v[142:143] op_sel_hi:[1,0,1]
	v_exp_f32_e32 v180, v180
	v_pk_fma_f32 v[174:175], v[152:153], s[98:99], v[144:145] op_sel_hi:[1,0,0]
	v_exp_f32_e32 v181, v181
	v_pk_fma_f32 v[174:175], v[152:153], v[174:175], s[90:91] op_sel_hi:[1,1,0]
	v_and_b32_e32 v183, 0x7fffffff, v157
	v_pk_fma_f32 v[174:175], v[152:153], v[174:175], s[4:5] op_sel_hi:[1,1,0]
	v_and_b32_e32 v182, 0x7fffffff, v156
	v_pk_fma_f32 v[174:175], v[152:153], v[174:175], s[78:79] op_sel_hi:[1,1,0]
	v_pk_fma_f32 v[182:183], v[182:183], s[96:97], 1.0 op_sel_hi:[1,0,0]
	v_pk_mul_f32 v[152:153], v[152:153], v[174:175]
	v_rcp_f32_e32 v182, v182
	v_rcp_f32_e32 v183, v183
	v_pk_mul_f32 v[152:153], v[180:181], v[152:153]
	v_cmp_gt_f32_e32 vcc, 0, v150
	v_pk_mul_f32 v[180:181], v[150:151], v[152:153]
	v_pk_fma_f32 v[152:153], v[150:151], v[152:153], v[150:151] neg_lo:[1,0,0] neg_hi:[1,0,0]
	v_pk_fma_f32 v[158:159], v[26:27], v[154:155], v[138:139] op_sel_hi:[1,0,1]
	v_pk_fma_f32 v[172:173], v[24:25], v[154:155], v[136:137] op_sel_hi:[1,0,1]
	v_pk_mul_f32 v[174:175], v[156:157], v[156:157]
	v_cndmask_b32_e32 v155, v152, v180, vcc
	v_cmp_gt_f32_e32 vcc, 0, v151
	v_pk_fma_f32 v[150:151], v[182:183], s[98:99], v[144:145] op_sel_hi:[1,0,0]
	s_nop 0
	v_cndmask_b32_e32 v180, v153, v181, vcc
	v_pk_mul_f32 v[152:153], v[174:175], s[74:75] op_sel_hi:[1,0]
	v_pk_fma_f32 v[150:151], v[182:183], v[150:151], s[90:91] op_sel_hi:[1,1,0]
	v_exp_f32_e32 v152, v152
	v_exp_f32_e32 v153, v153
	v_pk_fma_f32 v[150:151], v[182:183], v[150:151], s[4:5] op_sel_hi:[1,1,0]
	v_and_b32_e32 v175, 0x7fffffff, v173
	v_and_b32_e32 v174, 0x7fffffff, v172
	v_pk_fma_f32 v[150:151], v[182:183], v[150:151], s[78:79] op_sel_hi:[1,1,0]
	v_pk_fma_f32 v[174:175], v[174:175], s[96:97], 1.0 op_sel_hi:[1,0,0]
	v_pk_mul_f32 v[150:151], v[182:183], v[150:151]
	v_rcp_f32_e32 v174, v174
	v_rcp_f32_e32 v175, v175
	v_pk_mul_f32 v[150:151], v[152:153], v[150:151]
	v_cmp_gt_f32_e32 vcc, 0, v156
	v_pk_mul_f32 v[152:153], v[156:157], v[150:151]
	v_pk_fma_f32 v[150:151], v[156:157], v[150:151], v[156:157] neg_lo:[1,0,0] neg_hi:[1,0,0]
	s_nop 0
	v_cndmask_b32_e32 v181, v150, v152, vcc
	v_cmp_gt_f32_e32 vcc, 0, v157
	v_pk_mul_f32 v[156:157], v[158:159], v[158:159]
	s_nop 0
	v_cndmask_b32_e32 v182, v151, v153, vcc
	v_pk_fma_f32 v[150:151], v[174:175], s[98:99], v[144:145] op_sel_hi:[1,0,0]
	v_pk_mul_f32 v[152:153], v[172:173], v[172:173]
; __device__ __forceinline__ unsigned cvt_pk_bf16(float lo, float hi) { unsigned r; asm volatile("v_cvt_pk_bf16_f32 %0, %1, %2" : "=v"(r) : "v"(lo), "v"(hi)); return r; }
; __device__ __forceinline__ f32x2 gelu_pk(f32x2 v) {
;     const f32x2 av = __builtin_elementwise_abs(v), d = av * 0.2316418882f + 1.0f;
;     f32x2 t; t.x = __builtin_amdgcn_rcpf(d.x); t.y = __builtin_amdgcn_rcpf(d.y);
;     f32x2 q = t * 0.5307027145f + (-0.7265760135f); q = q * t + 0.7107068705f; q = q * t + (-0.142248368f); q = q * t + 0.127414796f; q = q * t;
;     const f32x2 s = (v * v) * (-0.72134752044f);
;     f32x2 e; e.x = __builtin_amdgcn_exp2f(s.x); e.y = __builtin_amdgcn_exp2f(s.y);
;     const f32x2 m = v * (q * e), r = v - m;
;     f32x2 o; o.x = v.x < 0.f ? m.x : r.x; o.y = v.y < 0.f ? m.y : r.y; return o;
; }
;     static __device__ __forceinline__ void run(const f32x4 (&acc)[2][2][4][2], const Unit& u, int wr, int wc, int fr, int fq, bf16_t* O, int ldc, const float* ssqA, const float* bvec) {
;     ...
;             for (int m = 0; m < 4; ++m) { const int row = row0 + ai * HALF + m * 16; const float r = row_scale(ssqA, nullptr, row); bf16_t* rowp = O + ((unsigned)row * (unsigned)ldc + (unsigned)col0);
; #pragma unroll
;                 for (int bj = 0; bj < 2; ++bj) { const f32x4 v0 = acc[ai][bj][m][0] * r + bv[bj][0], v1 = acc[ai][bj][m][1] * r + bv[bj][1];
;                     const f32x2 a = gelu_pk((f32x2){v0[0], v0[1]}), b2 = gelu_pk((f32x2){v0[2], v0[3]}), c = gelu_pk((f32x2){v1[0], v1[1]}), d = gelu_pk((f32x2){v1[2], v1[3]});
;                     u32x4 w; w.x = cvt_pk_bf16(a.x, a.y); w.y = cvt_pk_bf16(b2.x, b2.y); w.z = cvt_pk_bf16(c.x, c.y); w.w = cvt_pk_bf16(d.x, d.y);
;                     *(u32x4*)(rowp + bj * HALF) = w; }
	v_pk_fma_f32 v[150:151], v[174:175], v[150:151], s[90:91] op_sel_hi:[1,1,0]
	v_pk_mul_f32 v[152:153], v[152:153], s[74:75] op_sel_hi:[1,0]
	v_pk_fma_f32 v[150:151], v[174:175], v[150:151], s[4:5] op_sel_hi:[1,1,0]
	v_exp_f32_e32 v152, v152
	v_exp_f32_e32 v153, v153
	v_pk_fma_f32 v[150:151], v[174:175], v[150:151], s[78:79] op_sel_hi:[1,1,0]
	v_cmp_gt_f32_e32 vcc, 0, v172
	v_pk_mul_f32 v[150:151], v[174:175], v[150:151]
	v_and_b32_e32 v175, 0x7fffffff, v159
	v_and_b32_e32 v174, 0x7fffffff, v158
	v_pk_fma_f32 v[174:175], v[174:175], s[96:97], 1.0 op_sel_hi:[1,0,0]
	v_pk_mul_f32 v[150:151], v[152:153], v[150:151]
	v_rcp_f32_e32 v174, v174
	v_rcp_f32_e32 v175, v175
	v_pk_mul_f32 v[152:153], v[172:173], v[150:151]
	v_pk_fma_f32 v[150:151], v[172:173], v[150:151], v[172:173] neg_lo:[1,0,0] neg_hi:[1,0,0]
	s_nop 0
	v_cndmask_b32_e32 v172, v150, v152, vcc
	v_cmp_gt_f32_e32 vcc, 0, v173
	s_nop 1
	v_cndmask_b32_e32 v173, v151, v153, vcc
	v_pk_fma_f32 v[150:151], v[174:175], s[98:99], v[144:145] op_sel_hi:[1,0,0]
	v_pk_mul_f32 v[152:153], v[156:157], s[74:75] op_sel_hi:[1,0]
	v_pk_fma_f32 v[150:151], v[174:175], v[150:151], s[90:91] op_sel_hi:[1,1,0]
	v_exp_f32_e32 v152, v152
	v_exp_f32_e32 v153, v153
	v_pk_fma_f32 v[150:151], v[174:175], v[150:151], s[4:5] op_sel_hi:[1,1,0]
	v_cmp_gt_f32_e32 vcc, 0, v158
	v_pk_fma_f32 v[150:151], v[174:175], v[150:151], s[78:79] op_sel_hi:[1,1,0]
	s_nop 0
	v_pk_mul_f32 v[150:151], v[174:175], v[150:151]
	s_nop 0
	v_pk_mul_f32 v[150:151], v[152:153], v[150:151]
	s_nop 0
	v_pk_mul_f32 v[152:153], v[158:159], v[150:151]
	v_pk_fma_f32 v[150:151], v[158:159], v[150:151], v[158:159] neg_lo:[1,0,0] neg_hi:[1,0,0]
	s_nop 0
	v_cndmask_b32_e32 v156, v150, v152, vcc
	v_cmp_gt_f32_e32 vcc, 0, v159
	v_cvt_pk_bf16_f32 v150, v155, v180
	v_pk_fma_f32 v[158:159], v[18:19], v[154:155], v[130:131] op_sel_hi:[1,0,1]
	s_nop 0
	v_cndmask_b32_e32 v153, v151, v153, vcc
	v_cvt_pk_bf16_f32 v151, v181, v182
	v_cvt_pk_bf16_f32 v152, v172, v173
	v_cvt_pk_bf16_f32 v153, v156, v153
	global_store_dwordx4 v[148:149], v[150:153], off
	v_pk_fma_f32 v[156:157], v[22:23], v[154:155], v[134:135] op_sel_hi:[1,0,1]
	s_nop 0
	v_pk_fma_f32 v[150:151], v[20:21], v[154:155], v[132:133] op_sel_hi:[1,0,1]
	v_and_b32_e32 v181, 0x7fffffff, v157
	v_and_b32_e32 v153, 0x7fffffff, v151
	v_and_b32_e32 v152, 0x7fffffff, v150
	v_pk_fma_f32 v[152:153], v[152:153], s[96:97], 1.0 op_sel_hi:[1,0,0]
	v_pk_mul_f32 v[174:175], v[150:151], v[150:151]
	v_rcp_f32_e32 v152, v152
	v_rcp_f32_e32 v153, v153
	v_pk_mul_f32 v[174:175], v[174:175], s[74:75] op_sel_hi:[1,0]
	v_and_b32_e32 v180, 0x7fffffff, v156
	v_exp_f32_e32 v174, v174
	v_pk_fma_f32 v[172:173], v[152:153], s[98:99], v[144:145] op_sel_hi:[1,0,0]
	v_exp_f32_e32 v175, v175
	v_pk_fma_f32 v[172:173], v[152:153], v[172:173], s[90:91] op_sel_hi:[1,1,0]
	v_pk_fma_f32 v[180:181], v[180:181], s[96:97], 1.0 op_sel_hi:[1,0,0]
	v_pk_fma_f32 v[172:173], v[152:153], v[172:173], s[4:5] op_sel_hi:[1,1,0]
	v_rcp_f32_e32 v180, v180
	v_pk_fma_f32 v[172:173], v[152:153], v[172:173], s[78:79] op_sel_hi:[1,1,0]
	v_rcp_f32_e32 v181, v181
	v_pk_mul_f32 v[152:153], v[152:153], v[172:173]
	v_cmp_gt_f32_e32 vcc, 0, v150
	v_pk_mul_f32 v[152:153], v[174:175], v[152:153]
	v_pk_mul_f32 v[172:173], v[156:157], v[156:157]
	v_pk_mul_f32 v[174:175], v[150:151], v[152:153]
	v_pk_fma_f32 v[152:153], v[150:151], v[152:153], v[150:151] neg_lo:[1,0,0] neg_hi:[1,0,0]
	v_pk_fma_f32 v[154:155], v[16:17], v[154:155], v[128:129] op_sel_hi:[1,0,1]
	v_cndmask_b32_e32 v174, v152, v174, vcc
	v_cmp_gt_f32_e32 vcc, 0, v151
	v_pk_fma_f32 v[150:151], v[180:181], s[98:99], v[144:145] op_sel_hi:[1,0,0]
	s_nop 0
	v_cndmask_b32_e32 v175, v153, v175, vcc
	v_pk_mul_f32 v[152:153], v[172:173], s[74:75] op_sel_hi:[1,0]
	v_pk_fma_f32 v[150:151], v[180:181], v[150:151], s[90:91] op_sel_hi:[1,1,0]
	v_exp_f32_e32 v152, v152
	v_exp_f32_e32 v153, v153
	v_pk_fma_f32 v[150:151], v[180:181], v[150:151], s[4:5] op_sel_hi:[1,1,0]
	v_and_b32_e32 v173, 0x7fffffff, v155
	v_and_b32_e32 v172, 0x7fffffff, v154
	v_pk_fma_f32 v[150:151], v[180:181], v[150:151], s[78:79] op_sel_hi:[1,1,0]
	v_pk_fma_f32 v[172:173], v[172:173], s[96:97], 1.0 op_sel_hi:[1,0,0]
	v_pk_mul_f32 v[150:151], v[180:181], v[150:151]
	v_rcp_f32_e32 v172, v172
	v_rcp_f32_e32 v173, v173
	v_pk_mul_f32 v[150:151], v[152:153], v[150:151]
	v_cmp_gt_f32_e32 vcc, 0, v156
	v_pk_mul_f32 v[152:153], v[156:157], v[150:151]
	v_pk_fma_f32 v[150:151], v[156:157], v[150:151], v[156:157] neg_lo:[1,0,0] neg_hi:[1,0,0]
	s_nop 0
	v_cndmask_b32_e32 v180, v150, v152, vcc
	v_cmp_gt_f32_e32 vcc, 0, v157
	v_pk_mul_f32 v[156:157], v[158:159], v[158:159]
	s_nop 0
	v_cndmask_b32_e32 v181, v151, v153, vcc
	v_pk_fma_f32 v[150:151], v[172:173], s[98:99], v[144:145] op_sel_hi:[1,0,0]
	v_pk_mul_f32 v[152:153], v[154:155], v[154:155]
	v_pk_fma_f32 v[150:151], v[172:173], v[150:151], s[90:91] op_sel_hi:[1,1,0]
	v_pk_mul_f32 v[152:153], v[152:153], s[74:75] op_sel_hi:[1,0]
	v_pk_fma_f32 v[150:151], v[172:173], v[150:151], s[4:5] op_sel_hi:[1,1,0]
	v_exp_f32_e32 v152, v152
	v_exp_f32_e32 v153, v153
	v_pk_fma_f32 v[150:151], v[172:173], v[150:151], s[78:79] op_sel_hi:[1,1,0]
	v_cmp_gt_f32_e32 vcc, 0, v154
	v_pk_mul_f32 v[150:151], v[172:173], v[150:151]
	v_and_b32_e32 v173, 0x7fffffff, v159
	v_and_b32_e32 v172, 0x7fffffff, v158
	v_pk_fma_f32 v[172:173], v[172:173], s[96:97], 1.0 op_sel_hi:[1,0,0]
	v_pk_mul_f32 v[150:151], v[152:153], v[150:151]
	v_rcp_f32_e32 v172, v172
	v_rcp_f32_e32 v173, v173
	v_pk_mul_f32 v[152:153], v[154:155], v[150:151]
	v_pk_fma_f32 v[150:151], v[154:155], v[150:151], v[154:155] neg_lo:[1,0,0] neg_hi:[1,0,0]
	s_nop 0
	v_cndmask_b32_e32 v154, v150, v152, vcc
	v_cmp_gt_f32_e32 vcc, 0, v155
	s_nop 1
	v_cndmask_b32_e32 v155, v151, v153, vcc
	v_pk_fma_f32 v[150:151], v[172:173], s[98:99], v[144:145] op_sel_hi:[1,0,0]
	v_pk_mul_f32 v[152:153], v[156:157], s[74:75] op_sel_hi:[1,0]
	v_pk_fma_f32 v[150:151], v[172:173], v[150:151], s[90:91] op_sel_hi:[1,1,0]
	v_exp_f32_e32 v152, v152
	v_exp_f32_e32 v153, v153
	v_pk_fma_f32 v[150:151], v[172:173], v[150:151], s[4:5] op_sel_hi:[1,1,0]
	v_cmp_gt_f32_e32 vcc, 0, v158
	v_pk_fma_f32 v[150:151], v[172:173], v[150:151], s[78:79] op_sel_hi:[1,1,0]
	s_nop 0
	v_pk_mul_f32 v[150:151], v[172:173], v[150:151]
	s_nop 0
	v_pk_mul_f32 v[150:151], v[152:153], v[150:151]
	s_nop 0
	v_pk_mul_f32 v[152:153], v[158:159], v[150:151]
	v_pk_fma_f32 v[150:151], v[158:159], v[150:151], v[158:159] neg_lo:[1,0,0] neg_hi:[1,0,0]
	s_nop 0
	v_cndmask_b32_e32 v156, v150, v152, vcc
	v_cmp_gt_f32_e32 vcc, 0, v159
	v_cvt_pk_bf16_f32 v150, v174, v175
	s_nop 1
	v_cndmask_b32_e32 v153, v151, v153, vcc
	v_cvt_pk_bf16_f32 v151, v180, v181
	v_cvt_pk_bf16_f32 v152, v154, v155
	v_cvt_pk_bf16_f32 v153, v156, v153
	global_store_dwordx4 v[148:149], v[150:153], off offset:256
	s_nop 0
	s_waitcnt vmcnt(16)
; __device__ __forceinline__ unsigned cvt_pk_bf16(float lo, float hi) { unsigned r; asm volatile("v_cvt_pk_bf16_f32 %0, %1, %2" : "=v"(r) : "v"(lo), "v"(hi)); return r; }
; __device__ __forceinline__ f32x2 gelu_pk(f32x2 v) {
;     const f32x2 av = __builtin_elementwise_abs(v), d = av * 0.2316418882f + 1.0f;
;     f32x2 t; t.x = __builtin_amdgcn_rcpf(d.x); t.y = __builtin_amdgcn_rcpf(d.y);
;     f32x2 q = t * 0.5307027145f + (-0.7265760135f); q = q * t + 0.7107068705f; q = q * t + (-0.142248368f); q = q * t + 0.127414796f; q = q * t;
;     const f32x2 s = (v * v) * (-0.72134752044f);
;     f32x2 e; e.x = __builtin_amdgcn_exp2f(s.x); e.y = __builtin_amdgcn_exp2f(s.y);
;     const f32x2 m = v * (q * e), r = v - m;
;     f32x2 o; o.x = v.x < 0.f ? m.x : r.x; o.y = v.y < 0.f ? m.y : r.y; return o;
; }
;     static __device__ __forceinline__ void run(const f32x4 (&acc)[2][2][4][2], const Unit& u, int wr, int wc, int fr, int fq, bf16_t* O, int ldc, const float* ssqA, const float* bvec) {
;     ...
;             for (int m = 0; m < 4; ++m) { const int row = row0 + ai * HALF + m * 16; const float r = row_scale(ssqA, nullptr, row); bf16_t* rowp = O + ((unsigned)row * (unsigned)ldc + (unsigned)col0);
; #pragma unroll
;                 for (int bj = 0; bj < 2; ++bj) { const f32x4 v0 = acc[ai][bj][m][0] * r + bv[bj][0], v1 = acc[ai][bj][m][1] * r + bv[bj][1];
;                     const f32x2 a = gelu_pk((f32x2){v0[0], v0[1]}), b2 = gelu_pk((f32x2){v0[2], v0[3]}), c = gelu_pk((f32x2){v1[0], v1[1]}), d = gelu_pk((f32x2){v1[2], v1[3]});
;                     u32x4 w; w.x = cvt_pk_bf16(a.x, a.y); w.y = cvt_pk_bf16(b2.x, b2.y); w.z = cvt_pk_bf16(c.x, c.y); w.w = cvt_pk_bf16(d.x, d.y);
;                     *(u32x4*)(rowp + bj * HALF) = w; }
	v_fmamk_f32 v146, v204, 0x3a800000, v222
	v_rsq_f32_e32 v148, v146
	v_lshl_add_u64 v[146:147], v[176:177], 1, s[2:3]
	v_pk_fma_f32 v[140:141], v[12:13], v[148:149], v[140:141] op_sel_hi:[1,0,1]
	s_nop 0
	v_and_b32_e32 v151, 0x7fffffff, v141
	v_and_b32_e32 v150, 0x7fffffff, v140
	v_pk_fma_f32 v[150:151], v[150:151], s[96:97], 1.0 op_sel_hi:[1,0,0]
	v_pk_mul_f32 v[154:155], v[140:141], v[140:141]
	v_rcp_f32_e32 v150, v150
	v_rcp_f32_e32 v151, v151
	v_pk_mul_f32 v[154:155], v[154:155], s[74:75] op_sel_hi:[1,0]
	v_pk_fma_f32 v[142:143], v[14:15], v[148:149], v[142:143] op_sel_hi:[1,0,1]
	v_exp_f32_e32 v154, v154
	v_pk_fma_f32 v[152:153], v[150:151], s[98:99], v[144:145] op_sel_hi:[1,0,0]
	v_exp_f32_e32 v155, v155
	v_pk_fma_f32 v[152:153], v[150:151], v[152:153], s[90:91] op_sel_hi:[1,1,0]
	v_and_b32_e32 v157, 0x7fffffff, v143
	v_pk_fma_f32 v[152:153], v[150:151], v[152:153], s[4:5] op_sel_hi:[1,1,0]
	v_and_b32_e32 v156, 0x7fffffff, v142
	v_pk_fma_f32 v[152:153], v[150:151], v[152:153], s[78:79] op_sel_hi:[1,1,0]
	v_pk_fma_f32 v[156:157], v[156:157], s[96:97], 1.0 op_sel_hi:[1,0,0]
	v_pk_mul_f32 v[150:151], v[150:151], v[152:153]
	v_rcp_f32_e32 v156, v156
	v_rcp_f32_e32 v157, v157
	v_pk_mul_f32 v[150:151], v[154:155], v[150:151]
	v_cmp_gt_f32_e32 vcc, 0, v140
	v_pk_mul_f32 v[154:155], v[140:141], v[150:151]
	v_pk_fma_f32 v[150:151], v[140:141], v[150:151], v[140:141] neg_lo:[1,0,0] neg_hi:[1,0,0]
	v_pk_fma_f32 v[138:139], v[10:11], v[148:149], v[138:139] op_sel_hi:[1,0,1]
	v_pk_fma_f32 v[136:137], v[8:9], v[148:149], v[136:137] op_sel_hi:[1,0,1]
	v_pk_mul_f32 v[152:153], v[142:143], v[142:143]
	v_cndmask_b32_e32 v149, v150, v154, vcc
	v_cmp_gt_f32_e32 vcc, 0, v141
	v_pk_fma_f32 v[140:141], v[156:157], s[98:99], v[144:145] op_sel_hi:[1,0,0]
	v_pk_fma_f32 v[132:133], v[4:5], v[148:149], v[132:133] op_sel_hi:[1,0,1]
	v_cndmask_b32_e32 v154, v151, v155, vcc
	v_pk_mul_f32 v[150:151], v[152:153], s[74:75] op_sel_hi:[1,0]
	v_pk_fma_f32 v[140:141], v[156:157], v[140:141], s[90:91] op_sel_hi:[1,1,0]
	v_exp_f32_e32 v150, v150
	v_exp_f32_e32 v151, v151
	v_pk_fma_f32 v[140:141], v[156:157], v[140:141], s[4:5] op_sel_hi:[1,1,0]
	v_and_b32_e32 v153, 0x7fffffff, v137
	v_and_b32_e32 v152, 0x7fffffff, v136
	v_pk_fma_f32 v[140:141], v[156:157], v[140:141], s[78:79] op_sel_hi:[1,1,0]
	v_pk_fma_f32 v[152:153], v[152:153], s[96:97], 1.0 op_sel_hi:[1,0,0]
	v_pk_mul_f32 v[140:141], v[156:157], v[140:141]
	v_rcp_f32_e32 v152, v152
	v_rcp_f32_e32 v153, v153
	v_pk_mul_f32 v[140:141], v[150:151], v[140:141]
	v_cmp_gt_f32_e32 vcc, 0, v142
	v_pk_mul_f32 v[150:151], v[142:143], v[140:141]
	v_pk_fma_f32 v[140:141], v[142:143], v[140:141], v[142:143] neg_lo:[1,0,0] neg_hi:[1,0,0]
	v_pk_fma_f32 v[134:135], v[6:7], v[148:149], v[134:135] op_sel_hi:[1,0,1]
	v_cndmask_b32_e32 v155, v140, v150, vcc
	v_cmp_gt_f32_e32 vcc, 0, v143
	v_pk_mul_f32 v[142:143], v[136:137], v[136:137]
	v_pk_fma_f32 v[128:129], v[0:1], v[148:149], v[128:129] op_sel_hi:[1,0,1]
	v_cndmask_b32_e32 v156, v141, v151, vcc
	v_pk_fma_f32 v[140:141], v[152:153], s[98:99], v[144:145] op_sel_hi:[1,0,0]
	v_pk_mul_f32 v[142:143], v[142:143], s[74:75] op_sel_hi:[1,0]
	v_pk_fma_f32 v[140:141], v[152:153], v[140:141], s[90:91] op_sel_hi:[1,1,0]
	v_exp_f32_e32 v142, v142
	v_pk_fma_f32 v[140:141], v[152:153], v[140:141], s[4:5] op_sel_hi:[1,1,0]
	v_exp_f32_e32 v143, v143
	v_pk_fma_f32 v[140:141], v[152:153], v[140:141], s[78:79] op_sel_hi:[1,1,0]
	v_cmp_gt_f32_e32 vcc, 0, v136
	v_pk_mul_f32 v[140:141], v[152:153], v[140:141]
	v_and_b32_e32 v153, 0x7fffffff, v139
	v_and_b32_e32 v152, 0x7fffffff, v138
	v_pk_fma_f32 v[152:153], v[152:153], s[96:97], 1.0 op_sel_hi:[1,0,0]
	v_pk_mul_f32 v[140:141], v[142:143], v[140:141]
	v_rcp_f32_e32 v152, v152
	v_rcp_f32_e32 v153, v153
	v_pk_mul_f32 v[142:143], v[136:137], v[140:141]
	v_pk_fma_f32 v[140:141], v[136:137], v[140:141], v[136:137] neg_lo:[1,0,0] neg_hi:[1,0,0]
	v_pk_mul_f32 v[150:151], v[138:139], v[138:139]
	v_cndmask_b32_e32 v142, v140, v142, vcc
	v_cmp_gt_f32_e32 vcc, 0, v137
	v_pk_fma_f32 v[136:137], v[152:153], s[98:99], v[144:145] op_sel_hi:[1,0,0]
	v_pk_fma_f32 v[130:131], v[2:3], v[148:149], v[130:131] op_sel_hi:[1,0,1]
	v_cndmask_b32_e32 v143, v141, v143, vcc
	v_pk_mul_f32 v[140:141], v[150:151], s[74:75] op_sel_hi:[1,0]
	v_pk_fma_f32 v[136:137], v[152:153], v[136:137], s[90:91] op_sel_hi:[1,1,0]
	v_exp_f32_e32 v140, v140
	v_exp_f32_e32 v141, v141
	v_pk_fma_f32 v[136:137], v[152:153], v[136:137], s[4:5] op_sel_hi:[1,1,0]
	v_cmp_gt_f32_e32 vcc, 0, v138
	v_pk_fma_f32 v[136:137], v[152:153], v[136:137], s[78:79] op_sel_hi:[1,1,0]
	s_nop 0
	v_pk_mul_f32 v[136:137], v[152:153], v[136:137]
	s_nop 0
	v_pk_mul_f32 v[136:137], v[140:141], v[136:137]
	s_nop 0
	v_pk_mul_f32 v[140:141], v[138:139], v[136:137]
	v_pk_fma_f32 v[136:137], v[138:139], v[136:137], v[138:139] neg_lo:[1,0,0] neg_hi:[1,0,0]
; __device__ __forceinline__ unsigned cvt_pk_bf16(float lo, float hi) { unsigned r; asm volatile("v_cvt_pk_bf16_f32 %0, %1, %2" : "=v"(r) : "v"(lo), "v"(hi)); return r; }
; __device__ __forceinline__ f32x2 gelu_pk(f32x2 v) {
;     const f32x2 av = __builtin_elementwise_abs(v), d = av * 0.2316418882f + 1.0f;
;     f32x2 t; t.x = __builtin_amdgcn_rcpf(d.x); t.y = __builtin_amdgcn_rcpf(d.y);
;     f32x2 q = t * 0.5307027145f + (-0.7265760135f); q = q * t + 0.7107068705f; q = q * t + (-0.142248368f); q = q * t + 0.127414796f; q = q * t;
;     const f32x2 s = (v * v) * (-0.72134752044f);
;     f32x2 e; e.x = __builtin_amdgcn_exp2f(s.x); e.y = __builtin_amdgcn_exp2f(s.y);
;     const f32x2 m = v * (q * e), r = v - m;
;     f32x2 o; o.x = v.x < 0.f ? m.x : r.x; o.y = v.y < 0.f ? m.y : r.y; return o;
; }
;     static __device__ __forceinline__ void run(const f32x4 (&acc)[2][2][4][2], const Unit& u, int wr, int wc, int fr, int fq, bf16_t* O, int ldc, const float* ssqA, const float* bvec) {
;     ...
;                 for (int bj = 0; bj < 2; ++bj) { const f32x4 v0 = acc[ai][bj][m][0] * r + bv[bj][0], v1 = acc[ai][bj][m][1] * r + bv[bj][1];
;                     const f32x2 a = gelu_pk((f32x2){v0[0], v0[1]}), b2 = gelu_pk((f32x2){v0[2], v0[3]}), c = gelu_pk((f32x2){v1[0], v1[1]}), d = gelu_pk((f32x2){v1[2], v1[3]});
;                     u32x4 w; w.x = cvt_pk_bf16(a.x, a.y); w.y = cvt_pk_bf16(b2.x, b2.y); w.z = cvt_pk_bf16(c.x, c.y); w.w = cvt_pk_bf16(d.x, d.y);
;                     *(u32x4*)(rowp + bj * HALF) = w; }
;                 asm volatile("" ::: "memory"); }
	s_nop 0
	v_cndmask_b32_e32 v140, v136, v140, vcc
	v_cmp_gt_f32_e32 vcc, 0, v139
	v_cvt_pk_bf16_f32 v136, v149, v154
	s_nop 1
	v_cndmask_b32_e32 v139, v137, v141, vcc
	v_cvt_pk_bf16_f32 v137, v155, v156
	v_cvt_pk_bf16_f32 v138, v142, v143
	v_cvt_pk_bf16_f32 v139, v140, v139
	global_store_dwordx4 v[146:147], v[136:139], off
	v_pk_mul_f32 v[140:141], v[132:133], v[132:133]
	v_and_b32_e32 v143, 0x7fffffff, v135
	v_and_b32_e32 v137, 0x7fffffff, v133
	v_and_b32_e32 v136, 0x7fffffff, v132
	v_pk_fma_f32 v[136:137], v[136:137], s[96:97], 1.0 op_sel_hi:[1,0,0]
	v_pk_mul_f32 v[140:141], v[140:141], s[74:75] op_sel_hi:[1,0]
	v_rcp_f32_e32 v136, v136
	v_rcp_f32_e32 v137, v137
	v_exp_f32_e32 v140, v140
	v_exp_f32_e32 v141, v141
	v_and_b32_e32 v142, 0x7fffffff, v134
	v_pk_fma_f32 v[138:139], v[136:137], s[98:99], v[144:145] op_sel_hi:[1,0,0]
	v_pk_fma_f32 v[142:143], v[142:143], s[96:97], 1.0 op_sel_hi:[1,0,0]
	v_pk_fma_f32 v[138:139], v[136:137], v[138:139], s[90:91] op_sel_hi:[1,1,0]
	v_rcp_f32_e32 v142, v142
	v_pk_fma_f32 v[138:139], v[136:137], v[138:139], s[4:5] op_sel_hi:[1,1,0]
	v_rcp_f32_e32 v143, v143
	v_pk_fma_f32 v[138:139], v[136:137], v[138:139], s[78:79] op_sel_hi:[1,1,0]
	v_cmp_gt_f32_e32 vcc, 0, v132
	v_pk_mul_f32 v[136:137], v[136:137], v[138:139]
	v_pk_mul_f32 v[138:139], v[134:135], v[134:135]
	v_pk_mul_f32 v[136:137], v[140:141], v[136:137]
	s_nop 0
	v_pk_mul_f32 v[140:141], v[132:133], v[136:137]
	v_pk_fma_f32 v[136:137], v[132:133], v[136:137], v[132:133] neg_lo:[1,0,0] neg_hi:[1,0,0]
	s_nop 0
	v_cndmask_b32_e32 v140, v136, v140, vcc
	v_cmp_gt_f32_e32 vcc, 0, v133
	v_pk_fma_f32 v[132:133], v[142:143], s[98:99], v[144:145] op_sel_hi:[1,0,0]
	s_nop 0
	v_cndmask_b32_e32 v141, v137, v141, vcc
	v_pk_mul_f32 v[136:137], v[138:139], s[74:75] op_sel_hi:[1,0]
	v_pk_fma_f32 v[132:133], v[142:143], v[132:133], s[90:91] op_sel_hi:[1,1,0]
	v_exp_f32_e32 v136, v136
	v_exp_f32_e32 v137, v137
	v_pk_fma_f32 v[132:133], v[142:143], v[132:133], s[4:5] op_sel_hi:[1,1,0]
	v_and_b32_e32 v139, 0x7fffffff, v129
	v_and_b32_e32 v138, 0x7fffffff, v128
	v_pk_fma_f32 v[132:133], v[142:143], v[132:133], s[78:79] op_sel_hi:[1,1,0]
	v_pk_fma_f32 v[138:139], v[138:139], s[96:97], 1.0 op_sel_hi:[1,0,0]
	v_pk_mul_f32 v[132:133], v[142:143], v[132:133]
	v_rcp_f32_e32 v138, v138
	v_rcp_f32_e32 v139, v139
	v_pk_mul_f32 v[132:133], v[136:137], v[132:133]
	v_cmp_gt_f32_e32 vcc, 0, v134
	v_pk_mul_f32 v[136:137], v[134:135], v[132:133]
	v_pk_fma_f32 v[132:133], v[134:135], v[132:133], v[134:135] neg_lo:[1,0,0] neg_hi:[1,0,0]
	s_nop 0
	v_cndmask_b32_e32 v142, v132, v136, vcc
	v_cmp_gt_f32_e32 vcc, 0, v135
	v_pk_mul_f32 v[134:135], v[128:129], v[128:129]
	s_nop 0
	v_cndmask_b32_e32 v143, v133, v137, vcc
	v_pk_fma_f32 v[132:133], v[138:139], s[98:99], v[144:145] op_sel_hi:[1,0,0]
	v_pk_mul_f32 v[134:135], v[134:135], s[74:75] op_sel_hi:[1,0]
	v_pk_fma_f32 v[132:133], v[138:139], v[132:133], s[90:91] op_sel_hi:[1,1,0]
	v_exp_f32_e32 v134, v134
	v_pk_fma_f32 v[132:133], v[138:139], v[132:133], s[4:5] op_sel_hi:[1,1,0]
	v_exp_f32_e32 v135, v135
	v_pk_fma_f32 v[132:133], v[138:139], v[132:133], s[78:79] op_sel_hi:[1,1,0]
	v_cmp_gt_f32_e32 vcc, 0, v128
	v_pk_mul_f32 v[132:133], v[138:139], v[132:133]
	v_and_b32_e32 v139, 0x7fffffff, v131
	v_and_b32_e32 v138, 0x7fffffff, v130
	v_pk_fma_f32 v[138:139], v[138:139], s[96:97], 1.0 op_sel_hi:[1,0,0]
	v_pk_mul_f32 v[132:133], v[134:135], v[132:133]
	v_rcp_f32_e32 v138, v138
	v_rcp_f32_e32 v139, v139
	v_pk_mul_f32 v[134:135], v[128:129], v[132:133]
	v_pk_fma_f32 v[132:133], v[128:129], v[132:133], v[128:129] neg_lo:[1,0,0] neg_hi:[1,0,0]
	v_pk_mul_f32 v[136:137], v[130:131], v[130:131]
	v_cndmask_b32_e32 v134, v132, v134, vcc
	v_cmp_gt_f32_e32 vcc, 0, v129
	v_pk_fma_f32 v[128:129], v[138:139], s[98:99], v[144:145] op_sel_hi:[1,0,0]
	s_nop 0
	v_cndmask_b32_e32 v135, v133, v135, vcc
	v_pk_mul_f32 v[132:133], v[136:137], s[74:75] op_sel_hi:[1,0]
	v_pk_fma_f32 v[128:129], v[138:139], v[128:129], s[90:91] op_sel_hi:[1,1,0]
	v_exp_f32_e32 v132, v132
	v_exp_f32_e32 v133, v133
	v_pk_fma_f32 v[128:129], v[138:139], v[128:129], s[4:5] op_sel_hi:[1,1,0]
	v_cmp_gt_f32_e32 vcc, 0, v130
	v_pk_fma_f32 v[128:129], v[138:139], v[128:129], s[78:79] op_sel_hi:[1,1,0]
	s_nop 0
	v_pk_mul_f32 v[128:129], v[138:139], v[128:129]
	s_nop 0
	v_pk_mul_f32 v[128:129], v[132:133], v[128:129]
	s_nop 0
	v_pk_mul_f32 v[132:133], v[130:131], v[128:129]
	v_pk_fma_f32 v[128:129], v[130:131], v[128:129], v[130:131] neg_lo:[1,0,0] neg_hi:[1,0,0]
	s_nop 0
	v_cndmask_b32_e32 v132, v128, v132, vcc
	v_cmp_gt_f32_e32 vcc, 0, v131
	v_cvt_pk_bf16_f32 v128, v140, v141
	s_nop 1
	v_cndmask_b32_e32 v131, v129, v133, vcc
	v_cvt_pk_bf16_f32 v129, v142, v143
	v_cvt_pk_bf16_f32 v130, v134, v135
	v_cvt_pk_bf16_f32 v131, v132, v131
	global_store_dwordx4 v[146:147], v[128:131], off offset:256
